# compress second GEMM: all 16 weight loads and fragment reads issued up front (was a serial load-wait-MFMA chain)
# speedup vs baseline: 1.0073x; 1.0024x over previous
; __device__ __forceinline__ int mk_ltid() { int t = threadIdx.x; asm volatile("" : "+v"(t)); return t; }
; #define LAS __attribute__((address_space(3)))
; __device__ __forceinline__ void compress_unit(LAS unsigned char* lds, int u, const bf16_t* QKV, const float* pe_k, const float* pe_v,
;                                               const bf16_t* CW1  , const bf16_t* CW2  , bf16_t* KCMP, bf16_t* VCMP) {
;     const int tid = mk_ltid(), lane = tid & 63, w = __builtin_amdgcn_readfirstlane(tid >> 6), r32 = lane & 31, hi = lane >> 5;
;     const int kv = u >> 6, b = (u >> 4) & 3, g = (u >> 3) & 1, ch = u & 7;
;     const float* pe = kv ? pe_v : pe_k;
;     const bf16_t* W1 = CW1 + (size_t)kv * 256 * 2048; const bf16_t* W2 = CW2 + (size_t)kv * 64 * 256;
;     bf16_t* OUT = (kv ? VCMP : KCMP) + (size_t)((b * 2 + g) * 256 + ch * 32) * 64;
;     const int n = ch * 32 + r32;
;     const bf16_t* Ag = QKV + (size_t)(b * SEQ + 16 * n) * EVEN_PAD + (kv ? E_VC : E_KC) + g * 64 + hi * 8;
;     const bf16_t* Bg = W1 + (size_t)(32 * w + r32) * 2048 + hi * 8;
;     LAS bf16_t* HID = (LAS bf16_t*)lds;
;     LAS float* PE = (LAS float*)(lds + 20480);
;     v16f acc;
; #pragma unroll
;     for (int r = 0; r < 16; ++r) acc[r] = 0.f;
;     __syncthreads();
;     *(LAS v4f*)(PE + tid * 4) = *(const v4f*)(pe + tid * 4);
;     __syncthreads();
; #pragma unroll 8
;     for (int st = 0; st < 128; ++st) {
;         const int li = st >> 2, d0 = (st & 3) * 16;
;         const v4u ar = *(const v4u*)(Ag + (size_t)li * EVEN_PAD + d0);
;         const v4f pa = *(const LAS v4f*)(PE + li * 64 + d0 + hi * 8), pb = *(const LAS v4f*)(PE + li * 64 + d0 + hi * 8 + 4);
;         const v8s bfr = *(const v8s*)(Bg + st * 16);
;         v4u aw;
;         aw.x = pkbf(__uint_as_float(ar.x << 16) + pa.x, __uint_as_float(ar.x & 0xffff0000u) + pa.y);
;         aw.y = pkbf(__uint_as_float(ar.y << 16) + pa.z, __uint_as_float(ar.y & 0xffff0000u) + pa.w);
;         aw.z = pkbf(__uint_as_float(ar.z << 16) + pb.x, __uint_as_float(ar.z & 0xffff0000u) + pb.y);
;         aw.w = pkbf(__uint_as_float(ar.w << 16) + pb.z, __uint_as_float(ar.w & 0xffff0000u) + pb.w);
.LBB0_411:
	v_mov_b32_e32 v0, v202
	s_ashr_i32 s12, s18, 6
	v_readfirstlane_b32 s10, v0
	s_ashr_i32 s29, s10, 6
	s_bfe_u32 s11, s18, 0x20004
	s_ashr_i32 s13, s12, 31
	s_lshl_b32 s10, s18, 5
	s_lshr_b32 s28, s18, 3
	s_lshl_b64 s[16:17], s[12:13], 20
	s_and_b32 s27, s10, 0xe0
	s_lshl_b32 s30, s11, 12
	s_lshl_b32 s10, s29, 5
	v_and_b32_e32 v41, 31, v0
	s_cmp_lt_u32 s18, 64
	s_cselect_b64 s[14:15], -1, 0
	v_or_b32_e32 v2, s27, v41
	v_lshl_or_b32 v2, v2, 4, s30
	s_and_b64 s[30:31], s[14:15], exec
	s_cselect_b32 s30, s4, s6
	s_movk_i32 s34, 0x1400
	v_mul_u32_u24_e32 v6, 0xe00, v2
	s_cselect_b32 s31, s5, s7
	s_cselect_b32 s34, s34, 0x1500
	s_add_u32 s30, s30, s8
	v_lshlrev_b32_e32 v2, 2, v0
	s_addc_u32 s31, s31, s9
	v_ashrrev_i32_e32 v3, 31, v2
	v_lshl_add_u64 v[2:3], v[2:3], 2, s[30:31]
	s_barrier
	global_load_dwordx4 v[2:5], v[2:3], off
	v_bfe_u32 v40, v0, 5, 1
	v_readlane_b32 s30, v254, 61
	v_lshl_add_u32 v0, v0, 4, 0
	v_or_b32_e32 v34, s10, v41
	v_lshl_add_u32 v42, v40, 5, s30
	s_lshl_b32 s30, s18, 4
	s_and_b32 s30, s30, 0x80
	s_or_b32 s30, s30, s34
	s_add_u32 s30, s0, s30
	s_addc_u32 s31, s1, 0
	v_ashrrev_i32_e32 v35, 31, v34
	s_add_u32 s16, s25, s16
	s_addc_u32 s17, s26, s17
	s_waitcnt vmcnt(0)
	ds_write_b128 v0, v[2:5] offset:20480
	v_lshlrev_b32_e32 v2, 1, v6
	v_mov_b32_e32 v3, v1
	v_lshl_add_u64 v[36:37], s[30:31], 0, v[2:3]
	v_lshlrev_b64 v[2:3], 12, v[34:35]
	v_lshl_add_u64 v[38:39], s[16:17], 0, v[2:3]
	v_mov_b32_e32 v2, 0
	v_lshlrev_b32_e32 v0, 4, v40
	s_mov_b32 s16, 0
	v_mov_b32_e32 v3, v2
	v_mov_b32_e32 v4, v2
	v_mov_b32_e32 v5, v2
	v_mov_b32_e32 v6, v2
	v_mov_b32_e32 v7, v2
	v_mov_b32_e32 v8, v2
	v_mov_b32_e32 v9, v2
	v_mov_b32_e32 v10, v2
	v_mov_b32_e32 v11, v2
	v_mov_b32_e32 v12, v2
	v_mov_b32_e32 v13, v2
	v_mov_b32_e32 v14, v2
	v_mov_b32_e32 v15, v2
	v_mov_b32_e32 v16, v2
	v_mov_b32_e32 v17, v2
	s_waitcnt lgkmcnt(0)
	s_barrier
	v_and_b32_e32 v64, 63, v202
	v_and_b32_e32 v65, 7, v64
	v_lshrrev_b32_e32 v64, 3, v64
	s_lshr_b32 s17, s10, 5
	s_lshl_b32 s34, s17, 6
	v_add_u32_e32 v66, s34, v64
	v_mul_u32_u24_e32 v66, 0x1c00, v66
	v_lshl_add_u32 v66, v65, 4, v66
	s_mul_i32 s34, s17, 0x4040
	s_add_i32 s34, s34, 28672
	v_lshlrev_b32_e32 v67, 7, v64
	v_lshl_add_u32 v67, v65, 4, v67
	v_add_u32_e32 v67, s34, v67
	v_lshlrev_b32_e32 v68, 8, v64
	v_lshl_add_u32 v68, v65, 5, v68
	v_add_u32_e32 v68, 0x5000, v68
	s_bfe_u32 s35, s18, 0x20004
	s_lshl_b32 s35, s35, 12
	s_and_b32 s36, s18, 7
	s_lshl_b32 s36, s36, 9
	s_add_i32 s35, s35, s36
	s_mul_i32 s35, s35, 0x1c00
	s_add_u32 s44, s30, s35
	s_addc_u32 s45, s31, 0
	s_add_u32 s44, s44, 0x1c800000
	s_addc_u32 s45, s45, 0
	global_load_dwordx4 v[104:107], v66, s[44:45]
	s_add_u32 s46, s44, 0xe000
	s_addc_u32 s47, s45, 0
	global_load_dwordx4 v[108:111], v66, s[46:47]
	s_add_u32 s46, s44, 0x1c000
	s_addc_u32 s47, s45, 0
	global_load_dwordx4 v[112:115], v66, s[46:47]
	s_add_u32 s46, s44, 0x2a000
	s_addc_u32 s47, s45, 0
	global_load_dwordx4 v[116:119], v66, s[46:47]
	s_add_u32 s46, s44, 0x1c000
	s_addc_u32 s47, s45, 0
	global_load_dwordx4 v[120:123], v66, s[46:47]
	s_add_u32 s46, s44, 0x2a000
	s_addc_u32 s47, s45, 0
	global_load_dwordx4 v[124:127], v66, s[46:47]
	s_add_u32 s46, s44, 0x38000
	s_addc_u32 s47, s45, 0
	global_load_dwordx4 v[128:131], v66, s[46:47]
	s_add_u32 s46, s44, 0x46000
	s_addc_u32 s47, s45, 0
	global_load_dwordx4 v[132:135], v66, s[46:47]
	s_add_u32 s46, s44, 0x38000
	s_addc_u32 s47, s45, 0
	global_load_dwordx4 v[136:139], v66, s[46:47]
	s_add_u32 s46, s44, 0x46000
	s_addc_u32 s47, s45, 0
	global_load_dwordx4 v[140:143], v66, s[46:47]
	s_add_u32 s46, s44, 0x54000
	s_addc_u32 s47, s45, 0
	global_load_dwordx4 v[144:147], v66, s[46:47]
	s_add_u32 s46, s44, 0x62000
	s_addc_u32 s47, s45, 0
	global_load_dwordx4 v[148:151], v66, s[46:47]
	s_add_u32 s46, s44, 0x54000
	s_addc_u32 s47, s45, 0
	global_load_dwordx4 v[152:155], v66, s[46:47]
	s_add_u32 s46, s44, 0x62000
	s_addc_u32 s47, s45, 0
	global_load_dwordx4 v[156:159], v66, s[46:47]
	s_add_u32 s46, s44, 0x70000
	s_addc_u32 s47, s45, 0
	global_load_dwordx4 v[160:163], v66, s[46:47]
	s_add_u32 s46, s44, 0x7e000
	s_addc_u32 s47, s45, 0
	global_load_dwordx4 v[164:167], v66, s[46:47]
	ds_read_b128 v[72:75], v68
	ds_read_b128 v[76:79], v68 offset:16
	ds_read_b128 v[80:83], v68 offset:2048
	ds_read_b128 v[84:87], v68 offset:2064
	ds_read_b128 v[88:91], v68 offset:4096
	ds_read_b128 v[92:95], v68 offset:4112
	ds_read_b128 v[96:99], v68 offset:6144
	ds_read_b128 v[100:103], v68 offset:6160
	s_waitcnt lgkmcnt(0)
	s_waitcnt vmcnt(15)
	v_lshlrev_b32_e32 v168, 16, v104
	v_and_b32_e32 v169, 0xffff0000, v104
	v_lshlrev_b32_e32 v170, 16, v105
	v_and_b32_e32 v171, 0xffff0000, v105
	v_pk_add_f32 v[168:169], v[72:73], v[168:169]
	v_pk_add_f32 v[170:171], v[74:75], v[170:171]
	v_cvt_pk_bf16_f32 v104, v168, v169
	v_cvt_pk_bf16_f32 v105, v170, v171
	v_lshlrev_b32_e32 v168, 16, v106
	v_and_b32_e32 v169, 0xffff0000, v106
	v_lshlrev_b32_e32 v170, 16, v107
	v_and_b32_e32 v171, 0xffff0000, v107
	v_pk_add_f32 v[168:169], v[76:77], v[168:169]
	v_pk_add_f32 v[170:171], v[78:79], v[170:171]
	v_cvt_pk_bf16_f32 v106, v168, v169
	v_cvt_pk_bf16_f32 v107, v170, v171
	ds_write_b128 v67, v[104:107]
	s_waitcnt vmcnt(14)
	v_lshlrev_b32_e32 v168, 16, v108
	v_and_b32_e32 v169, 0xffff0000, v108
	v_lshlrev_b32_e32 v170, 16, v109
	v_and_b32_e32 v171, 0xffff0000, v109
	v_pk_add_f32 v[168:169], v[80:81], v[168:169]
	v_pk_add_f32 v[170:171], v[82:83], v[170:171]
	v_cvt_pk_bf16_f32 v108, v168, v169
	v_cvt_pk_bf16_f32 v109, v170, v171
	v_lshlrev_b32_e32 v168, 16, v110
	v_and_b32_e32 v169, 0xffff0000, v110
	v_lshlrev_b32_e32 v170, 16, v111
	v_and_b32_e32 v171, 0xffff0000, v111
	v_pk_add_f32 v[168:169], v[84:85], v[168:169]
	v_pk_add_f32 v[170:171], v[86:87], v[170:171]
	v_cvt_pk_bf16_f32 v110, v168, v169
	v_cvt_pk_bf16_f32 v111, v170, v171
	ds_write_b128 v67, v[108:111] offset:1024
	s_waitcnt vmcnt(13)
; #define LAS __attribute__((address_space(3)))
; __device__ __forceinline__ void compress_unit(LAS unsigned char* lds, int u, const bf16_t* QKV, const float* pe_k, const float* pe_v,
;                                               const bf16_t* CW1  , const bf16_t* CW2  , bf16_t* KCMP, bf16_t* VCMP) {
;     ...
;         const v4u ar = *(const v4u*)(Ag + (size_t)li * EVEN_PAD + d0);
;         const v4f pa = *(const LAS v4f*)(PE + li * 64 + d0 + hi * 8), pb = *(const LAS v4f*)(PE + li * 64 + d0 + hi * 8 + 4);
;         const v8s bfr = *(const v8s*)(Bg + st * 16);
;         v4u aw;
;         aw.x = pkbf(__uint_as_float(ar.x << 16) + pa.x, __uint_as_float(ar.x & 0xffff0000u) + pa.y);
;         aw.y = pkbf(__uint_as_float(ar.y << 16) + pa.z, __uint_as_float(ar.y & 0xffff0000u) + pa.w);
;         aw.z = pkbf(__uint_as_float(ar.z << 16) + pb.x, __uint_as_float(ar.z & 0xffff0000u) + pb.y);
;         aw.w = pkbf(__uint_as_float(ar.w << 16) + pb.z, __uint_as_float(ar.w & 0xffff0000u) + pb.w);
	v_lshlrev_b32_e32 v168, 16, v112
	v_and_b32_e32 v169, 0xffff0000, v112
	v_lshlrev_b32_e32 v170, 16, v113
	v_and_b32_e32 v171, 0xffff0000, v113
	v_pk_add_f32 v[168:169], v[88:89], v[168:169]
	v_pk_add_f32 v[170:171], v[90:91], v[170:171]
	v_cvt_pk_bf16_f32 v112, v168, v169
	v_cvt_pk_bf16_f32 v113, v170, v171
	v_lshlrev_b32_e32 v168, 16, v114
	v_and_b32_e32 v169, 0xffff0000, v114
	v_lshlrev_b32_e32 v170, 16, v115
	v_and_b32_e32 v171, 0xffff0000, v115
	v_pk_add_f32 v[168:169], v[92:93], v[168:169]
	v_pk_add_f32 v[170:171], v[94:95], v[170:171]
	v_cvt_pk_bf16_f32 v114, v168, v169
	v_cvt_pk_bf16_f32 v115, v170, v171
	ds_write_b128 v67, v[112:115] offset:2048
	s_waitcnt vmcnt(12)
	v_lshlrev_b32_e32 v168, 16, v116
	v_and_b32_e32 v169, 0xffff0000, v116
	v_lshlrev_b32_e32 v170, 16, v117
	v_and_b32_e32 v171, 0xffff0000, v117
	v_pk_add_f32 v[168:169], v[96:97], v[168:169]
	v_pk_add_f32 v[170:171], v[98:99], v[170:171]
	v_cvt_pk_bf16_f32 v116, v168, v169
	v_cvt_pk_bf16_f32 v117, v170, v171
	v_lshlrev_b32_e32 v168, 16, v118
	v_and_b32_e32 v169, 0xffff0000, v118
	v_lshlrev_b32_e32 v170, 16, v119
	v_and_b32_e32 v171, 0xffff0000, v119
	v_pk_add_f32 v[168:169], v[100:101], v[168:169]
	v_pk_add_f32 v[170:171], v[102:103], v[170:171]
	v_cvt_pk_bf16_f32 v118, v168, v169
	v_cvt_pk_bf16_f32 v119, v170, v171
	ds_write_b128 v67, v[116:119] offset:3072
	s_waitcnt vmcnt(11)
	v_lshlrev_b32_e32 v168, 16, v120
	v_and_b32_e32 v169, 0xffff0000, v120
	v_lshlrev_b32_e32 v170, 16, v121
	v_and_b32_e32 v171, 0xffff0000, v121
	v_pk_add_f32 v[168:169], v[72:73], v[168:169]
	v_pk_add_f32 v[170:171], v[74:75], v[170:171]
	v_cvt_pk_bf16_f32 v120, v168, v169
	v_cvt_pk_bf16_f32 v121, v170, v171
	v_lshlrev_b32_e32 v168, 16, v122
	v_and_b32_e32 v169, 0xffff0000, v122
	v_lshlrev_b32_e32 v170, 16, v123
	v_and_b32_e32 v171, 0xffff0000, v123
	v_pk_add_f32 v[168:169], v[76:77], v[168:169]
	v_pk_add_f32 v[170:171], v[78:79], v[170:171]
	v_cvt_pk_bf16_f32 v122, v168, v169
	v_cvt_pk_bf16_f32 v123, v170, v171
	ds_write_b128 v67, v[120:123] offset:4112
	s_waitcnt vmcnt(10)
	v_lshlrev_b32_e32 v168, 16, v124
	v_and_b32_e32 v169, 0xffff0000, v124
	v_lshlrev_b32_e32 v170, 16, v125
	v_and_b32_e32 v171, 0xffff0000, v125
	v_pk_add_f32 v[168:169], v[80:81], v[168:169]
	v_pk_add_f32 v[170:171], v[82:83], v[170:171]
	v_cvt_pk_bf16_f32 v124, v168, v169
	v_cvt_pk_bf16_f32 v125, v170, v171
	v_lshlrev_b32_e32 v168, 16, v126
	v_and_b32_e32 v169, 0xffff0000, v126
	v_lshlrev_b32_e32 v170, 16, v127
	v_and_b32_e32 v171, 0xffff0000, v127
	v_pk_add_f32 v[168:169], v[84:85], v[168:169]
	v_pk_add_f32 v[170:171], v[86:87], v[170:171]
	v_cvt_pk_bf16_f32 v126, v168, v169
	v_cvt_pk_bf16_f32 v127, v170, v171
	ds_write_b128 v67, v[124:127] offset:5136
	s_waitcnt vmcnt(9)
	v_lshlrev_b32_e32 v168, 16, v128
	v_and_b32_e32 v169, 0xffff0000, v128
	v_lshlrev_b32_e32 v170, 16, v129
	v_and_b32_e32 v171, 0xffff0000, v129
	v_pk_add_f32 v[168:169], v[88:89], v[168:169]
	v_pk_add_f32 v[170:171], v[90:91], v[170:171]
	v_cvt_pk_bf16_f32 v128, v168, v169
	v_cvt_pk_bf16_f32 v129, v170, v171
	v_lshlrev_b32_e32 v168, 16, v130
	v_and_b32_e32 v169, 0xffff0000, v130
	v_lshlrev_b32_e32 v170, 16, v131
	v_and_b32_e32 v171, 0xffff0000, v131
	v_pk_add_f32 v[168:169], v[92:93], v[168:169]
	v_pk_add_f32 v[170:171], v[94:95], v[170:171]
	v_cvt_pk_bf16_f32 v130, v168, v169
	v_cvt_pk_bf16_f32 v131, v170, v171
	ds_write_b128 v67, v[128:131] offset:6160
	s_waitcnt vmcnt(8)
	v_lshlrev_b32_e32 v168, 16, v132
	v_and_b32_e32 v169, 0xffff0000, v132
	v_lshlrev_b32_e32 v170, 16, v133
	v_and_b32_e32 v171, 0xffff0000, v133
	v_pk_add_f32 v[168:169], v[96:97], v[168:169]
	v_pk_add_f32 v[170:171], v[98:99], v[170:171]
	v_cvt_pk_bf16_f32 v132, v168, v169
	v_cvt_pk_bf16_f32 v133, v170, v171
	v_lshlrev_b32_e32 v168, 16, v134
	v_and_b32_e32 v169, 0xffff0000, v134
	v_lshlrev_b32_e32 v170, 16, v135
	v_and_b32_e32 v171, 0xffff0000, v135
	v_pk_add_f32 v[168:169], v[100:101], v[168:169]
	v_pk_add_f32 v[170:171], v[102:103], v[170:171]
	v_cvt_pk_bf16_f32 v134, v168, v169
	v_cvt_pk_bf16_f32 v135, v170, v171
	ds_write_b128 v67, v[132:135] offset:7184
	s_waitcnt vmcnt(7)
	v_lshlrev_b32_e32 v168, 16, v136
	v_and_b32_e32 v169, 0xffff0000, v136
	v_lshlrev_b32_e32 v170, 16, v137
	v_and_b32_e32 v171, 0xffff0000, v137
	v_pk_add_f32 v[168:169], v[72:73], v[168:169]
	v_pk_add_f32 v[170:171], v[74:75], v[170:171]
	v_cvt_pk_bf16_f32 v136, v168, v169
	v_cvt_pk_bf16_f32 v137, v170, v171
	v_lshlrev_b32_e32 v168, 16, v138
	v_and_b32_e32 v169, 0xffff0000, v138
	v_lshlrev_b32_e32 v170, 16, v139
	v_and_b32_e32 v171, 0xffff0000, v139
	v_pk_add_f32 v[168:169], v[76:77], v[168:169]
	v_pk_add_f32 v[170:171], v[78:79], v[170:171]
	v_cvt_pk_bf16_f32 v138, v168, v169
	v_cvt_pk_bf16_f32 v139, v170, v171
	ds_write_b128 v67, v[136:139] offset:8224
	s_waitcnt vmcnt(6)
	v_lshlrev_b32_e32 v168, 16, v140
	v_and_b32_e32 v169, 0xffff0000, v140
	v_lshlrev_b32_e32 v170, 16, v141
	v_and_b32_e32 v171, 0xffff0000, v141
	v_pk_add_f32 v[168:169], v[80:81], v[168:169]
	v_pk_add_f32 v[170:171], v[82:83], v[170:171]
	v_cvt_pk_bf16_f32 v140, v168, v169
	v_cvt_pk_bf16_f32 v141, v170, v171
	v_lshlrev_b32_e32 v168, 16, v142
	v_and_b32_e32 v169, 0xffff0000, v142
	v_lshlrev_b32_e32 v170, 16, v143
	v_and_b32_e32 v171, 0xffff0000, v143
	v_pk_add_f32 v[168:169], v[84:85], v[168:169]
	v_pk_add_f32 v[170:171], v[86:87], v[170:171]
	v_cvt_pk_bf16_f32 v142, v168, v169
	v_cvt_pk_bf16_f32 v143, v170, v171
	ds_write_b128 v67, v[140:143] offset:9248
	s_waitcnt vmcnt(5)
; #define LAS __attribute__((address_space(3)))
; __device__ __forceinline__ void compress_unit(LAS unsigned char* lds, int u, const bf16_t* QKV, const float* pe_k, const float* pe_v,
;                                               const bf16_t* CW1  , const bf16_t* CW2  , bf16_t* KCMP, bf16_t* VCMP) {
;     ...
;         const v4u ar = *(const v4u*)(Ag + (size_t)li * EVEN_PAD + d0);
;         const v4f pa = *(const LAS v4f*)(PE + li * 64 + d0 + hi * 8), pb = *(const LAS v4f*)(PE + li * 64 + d0 + hi * 8 + 4);
;         const v8s bfr = *(const v8s*)(Bg + st * 16);
;         v4u aw;
;         aw.x = pkbf(__uint_as_float(ar.x << 16) + pa.x, __uint_as_float(ar.x & 0xffff0000u) + pa.y);
;         aw.y = pkbf(__uint_as_float(ar.y << 16) + pa.z, __uint_as_float(ar.y & 0xffff0000u) + pa.w);
;         aw.z = pkbf(__uint_as_float(ar.z << 16) + pb.x, __uint_as_float(ar.z & 0xffff0000u) + pb.y);
;         aw.w = pkbf(__uint_as_float(ar.w << 16) + pb.z, __uint_as_float(ar.w & 0xffff0000u) + pb.w);
	v_lshlrev_b32_e32 v168, 16, v144
	v_and_b32_e32 v169, 0xffff0000, v144
	v_lshlrev_b32_e32 v170, 16, v145
	v_and_b32_e32 v171, 0xffff0000, v145
	v_pk_add_f32 v[168:169], v[88:89], v[168:169]
	v_pk_add_f32 v[170:171], v[90:91], v[170:171]
	v_cvt_pk_bf16_f32 v144, v168, v169
	v_cvt_pk_bf16_f32 v145, v170, v171
	v_lshlrev_b32_e32 v168, 16, v146
	v_and_b32_e32 v169, 0xffff0000, v146
	v_lshlrev_b32_e32 v170, 16, v147
	v_and_b32_e32 v171, 0xffff0000, v147
	v_pk_add_f32 v[168:169], v[92:93], v[168:169]
	v_pk_add_f32 v[170:171], v[94:95], v[170:171]
	v_cvt_pk_bf16_f32 v146, v168, v169
	v_cvt_pk_bf16_f32 v147, v170, v171
	ds_write_b128 v67, v[144:147] offset:10272
	s_waitcnt vmcnt(4)
	v_lshlrev_b32_e32 v168, 16, v148
	v_and_b32_e32 v169, 0xffff0000, v148
	v_lshlrev_b32_e32 v170, 16, v149
	v_and_b32_e32 v171, 0xffff0000, v149
	v_pk_add_f32 v[168:169], v[96:97], v[168:169]
	v_pk_add_f32 v[170:171], v[98:99], v[170:171]
	v_cvt_pk_bf16_f32 v148, v168, v169
	v_cvt_pk_bf16_f32 v149, v170, v171
	v_lshlrev_b32_e32 v168, 16, v150
	v_and_b32_e32 v169, 0xffff0000, v150
	v_lshlrev_b32_e32 v170, 16, v151
	v_and_b32_e32 v171, 0xffff0000, v151
	v_pk_add_f32 v[168:169], v[100:101], v[168:169]
	v_pk_add_f32 v[170:171], v[102:103], v[170:171]
	v_cvt_pk_bf16_f32 v150, v168, v169
	v_cvt_pk_bf16_f32 v151, v170, v171
	ds_write_b128 v67, v[148:151] offset:11296
	s_waitcnt vmcnt(3)
	v_lshlrev_b32_e32 v168, 16, v152
	v_and_b32_e32 v169, 0xffff0000, v152
	v_lshlrev_b32_e32 v170, 16, v153
	v_and_b32_e32 v171, 0xffff0000, v153
	v_pk_add_f32 v[168:169], v[72:73], v[168:169]
	v_pk_add_f32 v[170:171], v[74:75], v[170:171]
	v_cvt_pk_bf16_f32 v152, v168, v169
	v_cvt_pk_bf16_f32 v153, v170, v171
	v_lshlrev_b32_e32 v168, 16, v154
	v_and_b32_e32 v169, 0xffff0000, v154
	v_lshlrev_b32_e32 v170, 16, v155
	v_and_b32_e32 v171, 0xffff0000, v155
	v_pk_add_f32 v[168:169], v[76:77], v[168:169]
	v_pk_add_f32 v[170:171], v[78:79], v[170:171]
	v_cvt_pk_bf16_f32 v154, v168, v169
	v_cvt_pk_bf16_f32 v155, v170, v171
	ds_write_b128 v67, v[152:155] offset:12336
	s_waitcnt vmcnt(2)
	v_lshlrev_b32_e32 v168, 16, v156
	v_and_b32_e32 v169, 0xffff0000, v156
	v_lshlrev_b32_e32 v170, 16, v157
	v_and_b32_e32 v171, 0xffff0000, v157
	v_pk_add_f32 v[168:169], v[80:81], v[168:169]
	v_pk_add_f32 v[170:171], v[82:83], v[170:171]
	v_cvt_pk_bf16_f32 v156, v168, v169
	v_cvt_pk_bf16_f32 v157, v170, v171
	v_lshlrev_b32_e32 v168, 16, v158
	v_and_b32_e32 v169, 0xffff0000, v158
	v_lshlrev_b32_e32 v170, 16, v159
	v_and_b32_e32 v171, 0xffff0000, v159
	v_pk_add_f32 v[168:169], v[84:85], v[168:169]
	v_pk_add_f32 v[170:171], v[86:87], v[170:171]
	v_cvt_pk_bf16_f32 v158, v168, v169
	v_cvt_pk_bf16_f32 v159, v170, v171
	ds_write_b128 v67, v[156:159] offset:13360
	s_waitcnt vmcnt(1)
	v_lshlrev_b32_e32 v168, 16, v160
	v_and_b32_e32 v169, 0xffff0000, v160
	v_lshlrev_b32_e32 v170, 16, v161
	v_and_b32_e32 v171, 0xffff0000, v161
	v_pk_add_f32 v[168:169], v[88:89], v[168:169]
	v_pk_add_f32 v[170:171], v[90:91], v[170:171]
	v_cvt_pk_bf16_f32 v160, v168, v169
	v_cvt_pk_bf16_f32 v161, v170, v171
	v_lshlrev_b32_e32 v168, 16, v162
	v_and_b32_e32 v169, 0xffff0000, v162
	v_lshlrev_b32_e32 v170, 16, v163
	v_and_b32_e32 v171, 0xffff0000, v163
	v_pk_add_f32 v[168:169], v[92:93], v[168:169]
	v_pk_add_f32 v[170:171], v[94:95], v[170:171]
	v_cvt_pk_bf16_f32 v162, v168, v169
	v_cvt_pk_bf16_f32 v163, v170, v171
	ds_write_b128 v67, v[160:163] offset:14384
	s_waitcnt vmcnt(0)
	v_lshlrev_b32_e32 v168, 16, v164
	v_and_b32_e32 v169, 0xffff0000, v164
	v_lshlrev_b32_e32 v170, 16, v165
	v_and_b32_e32 v171, 0xffff0000, v165
	v_pk_add_f32 v[168:169], v[96:97], v[168:169]
	v_pk_add_f32 v[170:171], v[98:99], v[170:171]
	v_cvt_pk_bf16_f32 v164, v168, v169
	v_cvt_pk_bf16_f32 v165, v170, v171
	v_lshlrev_b32_e32 v168, 16, v166
	v_and_b32_e32 v169, 0xffff0000, v166
	v_lshlrev_b32_e32 v170, 16, v167
	v_and_b32_e32 v171, 0xffff0000, v167
	v_pk_add_f32 v[168:169], v[100:101], v[168:169]
	v_pk_add_f32 v[170:171], v[102:103], v[170:171]
	v_cvt_pk_bf16_f32 v166, v168, v169
	v_cvt_pk_bf16_f32 v167, v170, v171
	ds_write_b128 v67, v[164:167] offset:15408
	v_lshl_add_u64 v[70:71], v[38:39], 0, v[0:1]
	v_mul_u32_u24_e32 v69, 0x1010, v41
	v_add_u32_e32 v69, v69, v0
	v_add_u32_e32 v69, 0x7000, v69
	global_load_dwordx4 v[72:75], v[70:71], off offset:-128
	global_load_dwordx4 v[76:79], v[70:71], off offset:-96
	global_load_dwordx4 v[80:83], v[70:71], off offset:-64
	global_load_dwordx4 v[84:87], v[70:71], off offset:-32
	global_load_dwordx4 v[88:91], v[70:71], off
	global_load_dwordx4 v[92:95], v[70:71], off offset:32
	global_load_dwordx4 v[96:99], v[70:71], off offset:64
	global_load_dwordx4 v[100:103], v[70:71], off offset:96
	global_load_dwordx4 v[168:171], v[70:71], off offset:128
	global_load_dwordx4 v[172:175], v[70:71], off offset:160
	global_load_dwordx4 v[176:179], v[70:71], off offset:192
	global_load_dwordx4 v[180:183], v[70:71], off offset:224
	global_load_dwordx4 v[184:187], v[70:71], off offset:256
	global_load_dwordx4 v[188:191], v[70:71], off offset:288
	global_load_dwordx4 v[192:195], v[70:71], off offset:320
	global_load_dwordx4 v[196:199], v[70:71], off offset:352
	s_waitcnt lgkmcnt(0)
	s_barrier
; #define LAS __attribute__((address_space(3)))
; __device__ __forceinline__ v16f mfma32(v8s a, v8s b, v16f c) { return __builtin_amdgcn_mfma_f32_32x32x16_bf16(a, b, c, 0, 0, 0); }
; __device__ __forceinline__ void compress_unit(LAS unsigned char* lds, int u, const bf16_t* QKV, const float* pe_k, const float* pe_v,
;                                               const bf16_t* CW1  , const bf16_t* CW2  , bf16_t* KCMP, bf16_t* VCMP) {
;     ...
;     for (int st = 0; st < 128; ++st) {
;         const int li = st >> 2, d0 = (st & 3) * 16;
;         const v4u ar = *(const v4u*)(Ag + (size_t)li * EVEN_PAD + d0);
;         const v4f pa = *(const LAS v4f*)(PE + li * 64 + d0 + hi * 8), pb = *(const LAS v4f*)(PE + li * 64 + d0 + hi * 8 + 4);
;         const v8s bfr = *(const v8s*)(Bg + st * 16);
;         v4u aw;
;         aw.x = pkbf(__uint_as_float(ar.x << 16) + pa.x, __uint_as_float(ar.x & 0xffff0000u) + pa.y);
;         aw.y = pkbf(__uint_as_float(ar.y << 16) + pa.z, __uint_as_float(ar.y & 0xffff0000u) + pa.w);
;         aw.z = pkbf(__uint_as_float(ar.z << 16) + pb.x, __uint_as_float(ar.z & 0xffff0000u) + pb.y);
;         aw.w = pkbf(__uint_as_float(ar.w << 16) + pb.z, __uint_as_float(ar.w & 0xffff0000u) + pb.w);
;         acc = mfma32(__builtin_bit_cast(v8s, aw), bfr, acc);
;     }
	ds_read_b128 v[104:107], v69
	ds_read_b128 v[108:111], v69 offset:32
	ds_read_b128 v[112:115], v69 offset:64
	ds_read_b128 v[116:119], v69 offset:96
	ds_read_b128 v[120:123], v69 offset:128
	ds_read_b128 v[124:127], v69 offset:160
	ds_read_b128 v[128:131], v69 offset:192
	ds_read_b128 v[132:135], v69 offset:224
	ds_read_b128 v[136:139], v69 offset:256
	ds_read_b128 v[140:143], v69 offset:288
	ds_read_b128 v[144:147], v69 offset:320
	ds_read_b128 v[148:151], v69 offset:352
	ds_read_b128 v[152:155], v69 offset:384
	ds_read_b128 v[156:159], v69 offset:416
	ds_read_b128 v[160:163], v69 offset:448
	ds_read_b128 v[164:167], v69 offset:480
	s_waitcnt lgkmcnt(8)
	s_waitcnt vmcnt(15)
	v_mfma_f32_32x32x16_bf16 v[2:17], v[104:107], v[72:75], v[2:17]
	s_waitcnt vmcnt(14)
	v_mfma_f32_32x32x16_bf16 v[2:17], v[108:111], v[76:79], v[2:17]
	s_waitcnt vmcnt(13)
	v_mfma_f32_32x32x16_bf16 v[2:17], v[112:115], v[80:83], v[2:17]
	s_waitcnt vmcnt(12)
	v_mfma_f32_32x32x16_bf16 v[2:17], v[116:119], v[84:87], v[2:17]
	s_waitcnt vmcnt(11)
	v_mfma_f32_32x32x16_bf16 v[2:17], v[120:123], v[88:91], v[2:17]
	s_waitcnt vmcnt(10)
	v_mfma_f32_32x32x16_bf16 v[2:17], v[124:127], v[92:95], v[2:17]
	s_waitcnt vmcnt(9)
	v_mfma_f32_32x32x16_bf16 v[2:17], v[128:131], v[96:99], v[2:17]
	s_waitcnt vmcnt(8)
	v_mfma_f32_32x32x16_bf16 v[2:17], v[132:135], v[100:103], v[2:17]
	global_load_dwordx4 v[72:75], v[70:71], off offset:384
	global_load_dwordx4 v[76:79], v[70:71], off offset:416
	global_load_dwordx4 v[80:83], v[70:71], off offset:448
	global_load_dwordx4 v[84:87], v[70:71], off offset:480
	global_load_dwordx4 v[88:91], v[70:71], off offset:512
	global_load_dwordx4 v[92:95], v[70:71], off offset:544
	global_load_dwordx4 v[96:99], v[70:71], off offset:576
	global_load_dwordx4 v[100:103], v[70:71], off offset:608
	ds_read_b128 v[104:107], v69 offset:512
	ds_read_b128 v[108:111], v69 offset:544
	ds_read_b128 v[112:115], v69 offset:576
	ds_read_b128 v[116:119], v69 offset:608
	ds_read_b128 v[120:123], v69 offset:640
	ds_read_b128 v[124:127], v69 offset:672
	ds_read_b128 v[128:131], v69 offset:704
	ds_read_b128 v[132:135], v69 offset:736
	s_waitcnt lgkmcnt(8)
	s_waitcnt vmcnt(15)
	v_mfma_f32_32x32x16_bf16 v[2:17], v[136:139], v[168:171], v[2:17]
	s_waitcnt vmcnt(14)
	v_mfma_f32_32x32x16_bf16 v[2:17], v[140:143], v[172:175], v[2:17]
	s_waitcnt vmcnt(13)
	v_mfma_f32_32x32x16_bf16 v[2:17], v[144:147], v[176:179], v[2:17]
	s_waitcnt vmcnt(12)
	v_mfma_f32_32x32x16_bf16 v[2:17], v[148:151], v[180:183], v[2:17]
	s_waitcnt vmcnt(11)
	v_mfma_f32_32x32x16_bf16 v[2:17], v[152:155], v[184:187], v[2:17]
	s_waitcnt vmcnt(10)
	v_mfma_f32_32x32x16_bf16 v[2:17], v[156:159], v[188:191], v[2:17]
	s_waitcnt vmcnt(9)
	v_mfma_f32_32x32x16_bf16 v[2:17], v[160:163], v[192:195], v[2:17]
	s_waitcnt vmcnt(8)
	v_mfma_f32_32x32x16_bf16 v[2:17], v[164:167], v[196:199], v[2:17]
	global_load_dwordx4 v[168:171], v[70:71], off offset:640
	global_load_dwordx4 v[172:175], v[70:71], off offset:672
	global_load_dwordx4 v[176:179], v[70:71], off offset:704
	global_load_dwordx4 v[180:183], v[70:71], off offset:736
	global_load_dwordx4 v[184:187], v[70:71], off offset:768
	global_load_dwordx4 v[188:191], v[70:71], off offset:800
	global_load_dwordx4 v[192:195], v[70:71], off offset:832
	global_load_dwordx4 v[196:199], v[70:71], off offset:864
	ds_read_b128 v[136:139], v69 offset:768
	ds_read_b128 v[140:143], v69 offset:800
	ds_read_b128 v[144:147], v69 offset:832
	ds_read_b128 v[148:151], v69 offset:864
	ds_read_b128 v[152:155], v69 offset:896
	ds_read_b128 v[156:159], v69 offset:928
	ds_read_b128 v[160:163], v69 offset:960
	ds_read_b128 v[164:167], v69 offset:992
	s_waitcnt lgkmcnt(8)
	s_waitcnt vmcnt(15)
	v_mfma_f32_32x32x16_bf16 v[2:17], v[104:107], v[72:75], v[2:17]
	s_waitcnt vmcnt(14)
	v_mfma_f32_32x32x16_bf16 v[2:17], v[108:111], v[76:79], v[2:17]
	s_waitcnt vmcnt(13)
	v_mfma_f32_32x32x16_bf16 v[2:17], v[112:115], v[80:83], v[2:17]
	s_waitcnt vmcnt(12)
	v_mfma_f32_32x32x16_bf16 v[2:17], v[116:119], v[84:87], v[2:17]
	s_waitcnt vmcnt(11)
	v_mfma_f32_32x32x16_bf16 v[2:17], v[120:123], v[88:91], v[2:17]
	s_waitcnt vmcnt(10)
	v_mfma_f32_32x32x16_bf16 v[2:17], v[124:127], v[92:95], v[2:17]
	s_waitcnt vmcnt(9)
	v_mfma_f32_32x32x16_bf16 v[2:17], v[128:131], v[96:99], v[2:17]
	s_waitcnt vmcnt(8)
	v_mfma_f32_32x32x16_bf16 v[2:17], v[132:135], v[100:103], v[2:17]
	global_load_dwordx4 v[72:75], v[70:71], off offset:896
	global_load_dwordx4 v[76:79], v[70:71], off offset:928
	global_load_dwordx4 v[80:83], v[70:71], off offset:960
	global_load_dwordx4 v[84:87], v[70:71], off offset:992
	global_load_dwordx4 v[88:91], v[70:71], off offset:1024
	global_load_dwordx4 v[92:95], v[70:71], off offset:1056
	global_load_dwordx4 v[96:99], v[70:71], off offset:1088
	global_load_dwordx4 v[100:103], v[70:71], off offset:1120
	ds_read_b128 v[104:107], v69 offset:1024
	ds_read_b128 v[108:111], v69 offset:1056
	ds_read_b128 v[112:115], v69 offset:1088
	ds_read_b128 v[116:119], v69 offset:1120
	ds_read_b128 v[120:123], v69 offset:1152
	ds_read_b128 v[124:127], v69 offset:1184
	ds_read_b128 v[128:131], v69 offset:1216
	ds_read_b128 v[132:135], v69 offset:1248
	s_waitcnt lgkmcnt(8)
	s_waitcnt vmcnt(15)
	v_mfma_f32_32x32x16_bf16 v[2:17], v[136:139], v[168:171], v[2:17]
	s_waitcnt vmcnt(14)
	v_mfma_f32_32x32x16_bf16 v[2:17], v[140:143], v[172:175], v[2:17]
	s_waitcnt vmcnt(13)
	v_mfma_f32_32x32x16_bf16 v[2:17], v[144:147], v[176:179], v[2:17]
	s_waitcnt vmcnt(12)
	v_mfma_f32_32x32x16_bf16 v[2:17], v[148:151], v[180:183], v[2:17]
	s_waitcnt vmcnt(11)
	v_mfma_f32_32x32x16_bf16 v[2:17], v[152:155], v[184:187], v[2:17]
	s_waitcnt vmcnt(10)
; #define LAS __attribute__((address_space(3)))
; __device__ __forceinline__ v16f mfma32(v8s a, v8s b, v16f c) { return __builtin_amdgcn_mfma_f32_32x32x16_bf16(a, b, c, 0, 0, 0); }
; __device__ __forceinline__ void compress_unit(LAS unsigned char* lds, int u, const bf16_t* QKV, const float* pe_k, const float* pe_v,
;                                               const bf16_t* CW1  , const bf16_t* CW2  , bf16_t* KCMP, bf16_t* VCMP) {
;     ...
;     for (int st = 0; st < 128; ++st) {
;         const int li = st >> 2, d0 = (st & 3) * 16;
;         const v4u ar = *(const v4u*)(Ag + (size_t)li * EVEN_PAD + d0);
;         const v4f pa = *(const LAS v4f*)(PE + li * 64 + d0 + hi * 8), pb = *(const LAS v4f*)(PE + li * 64 + d0 + hi * 8 + 4);
;         const v8s bfr = *(const v8s*)(Bg + st * 16);
;         v4u aw;
;         aw.x = pkbf(__uint_as_float(ar.x << 16) + pa.x, __uint_as_float(ar.x & 0xffff0000u) + pa.y);
;         aw.y = pkbf(__uint_as_float(ar.y << 16) + pa.z, __uint_as_float(ar.y & 0xffff0000u) + pa.w);
;         aw.z = pkbf(__uint_as_float(ar.z << 16) + pb.x, __uint_as_float(ar.z & 0xffff0000u) + pb.y);
;         aw.w = pkbf(__uint_as_float(ar.w << 16) + pb.z, __uint_as_float(ar.w & 0xffff0000u) + pb.w);
;         acc = mfma32(__builtin_bit_cast(v8s, aw), bfr, acc);
;     }
	v_mfma_f32_32x32x16_bf16 v[2:17], v[156:159], v[188:191], v[2:17]
	s_waitcnt vmcnt(9)
	v_mfma_f32_32x32x16_bf16 v[2:17], v[160:163], v[192:195], v[2:17]
	s_waitcnt vmcnt(8)
	v_mfma_f32_32x32x16_bf16 v[2:17], v[164:167], v[196:199], v[2:17]
	global_load_dwordx4 v[168:171], v[70:71], off offset:1152
	global_load_dwordx4 v[172:175], v[70:71], off offset:1184
	global_load_dwordx4 v[176:179], v[70:71], off offset:1216
	global_load_dwordx4 v[180:183], v[70:71], off offset:1248
	global_load_dwordx4 v[184:187], v[70:71], off offset:1280
	global_load_dwordx4 v[188:191], v[70:71], off offset:1312
	global_load_dwordx4 v[192:195], v[70:71], off offset:1344
	global_load_dwordx4 v[196:199], v[70:71], off offset:1376
	ds_read_b128 v[136:139], v69 offset:1280
	ds_read_b128 v[140:143], v69 offset:1312
	ds_read_b128 v[144:147], v69 offset:1344
	ds_read_b128 v[148:151], v69 offset:1376
	ds_read_b128 v[152:155], v69 offset:1408
	ds_read_b128 v[156:159], v69 offset:1440
	ds_read_b128 v[160:163], v69 offset:1472
	ds_read_b128 v[164:167], v69 offset:1504
	s_waitcnt lgkmcnt(8)
	s_waitcnt vmcnt(15)
	v_mfma_f32_32x32x16_bf16 v[2:17], v[104:107], v[72:75], v[2:17]
	s_waitcnt vmcnt(14)
	v_mfma_f32_32x32x16_bf16 v[2:17], v[108:111], v[76:79], v[2:17]
	s_waitcnt vmcnt(13)
	v_mfma_f32_32x32x16_bf16 v[2:17], v[112:115], v[80:83], v[2:17]
	s_waitcnt vmcnt(12)
	v_mfma_f32_32x32x16_bf16 v[2:17], v[116:119], v[84:87], v[2:17]
	s_waitcnt vmcnt(11)
	v_mfma_f32_32x32x16_bf16 v[2:17], v[120:123], v[88:91], v[2:17]
	s_waitcnt vmcnt(10)
	v_mfma_f32_32x32x16_bf16 v[2:17], v[124:127], v[92:95], v[2:17]
	s_waitcnt vmcnt(9)
	v_mfma_f32_32x32x16_bf16 v[2:17], v[128:131], v[96:99], v[2:17]
	s_waitcnt vmcnt(8)
	v_mfma_f32_32x32x16_bf16 v[2:17], v[132:135], v[100:103], v[2:17]
	global_load_dwordx4 v[72:75], v[70:71], off offset:1408
	global_load_dwordx4 v[76:79], v[70:71], off offset:1440
	global_load_dwordx4 v[80:83], v[70:71], off offset:1472
	global_load_dwordx4 v[84:87], v[70:71], off offset:1504
	global_load_dwordx4 v[88:91], v[70:71], off offset:1536
	global_load_dwordx4 v[92:95], v[70:71], off offset:1568
	global_load_dwordx4 v[96:99], v[70:71], off offset:1600
	global_load_dwordx4 v[100:103], v[70:71], off offset:1632
	ds_read_b128 v[104:107], v69 offset:1536
	ds_read_b128 v[108:111], v69 offset:1568
	ds_read_b128 v[112:115], v69 offset:1600
	ds_read_b128 v[116:119], v69 offset:1632
	ds_read_b128 v[120:123], v69 offset:1664
	ds_read_b128 v[124:127], v69 offset:1696
	ds_read_b128 v[128:131], v69 offset:1728
	ds_read_b128 v[132:135], v69 offset:1760
	s_waitcnt lgkmcnt(8)
	s_waitcnt vmcnt(15)
	v_mfma_f32_32x32x16_bf16 v[2:17], v[136:139], v[168:171], v[2:17]
	s_waitcnt vmcnt(14)
	v_mfma_f32_32x32x16_bf16 v[2:17], v[140:143], v[172:175], v[2:17]
	s_waitcnt vmcnt(13)
	v_mfma_f32_32x32x16_bf16 v[2:17], v[144:147], v[176:179], v[2:17]
	s_waitcnt vmcnt(12)
	v_mfma_f32_32x32x16_bf16 v[2:17], v[148:151], v[180:183], v[2:17]
	s_waitcnt vmcnt(11)
	v_mfma_f32_32x32x16_bf16 v[2:17], v[152:155], v[184:187], v[2:17]
	s_waitcnt vmcnt(10)
	v_mfma_f32_32x32x16_bf16 v[2:17], v[156:159], v[188:191], v[2:17]
	s_waitcnt vmcnt(9)
	v_mfma_f32_32x32x16_bf16 v[2:17], v[160:163], v[192:195], v[2:17]
	s_waitcnt vmcnt(8)
	v_mfma_f32_32x32x16_bf16 v[2:17], v[164:167], v[196:199], v[2:17]
	global_load_dwordx4 v[168:171], v[70:71], off offset:1664
	global_load_dwordx4 v[172:175], v[70:71], off offset:1696
	global_load_dwordx4 v[176:179], v[70:71], off offset:1728
	global_load_dwordx4 v[180:183], v[70:71], off offset:1760
	global_load_dwordx4 v[184:187], v[70:71], off offset:1792
	global_load_dwordx4 v[188:191], v[70:71], off offset:1824
	global_load_dwordx4 v[192:195], v[70:71], off offset:1856
	global_load_dwordx4 v[196:199], v[70:71], off offset:1888
	ds_read_b128 v[136:139], v69 offset:1792
	ds_read_b128 v[140:143], v69 offset:1824
	ds_read_b128 v[144:147], v69 offset:1856
	ds_read_b128 v[148:151], v69 offset:1888
	ds_read_b128 v[152:155], v69 offset:1920
	ds_read_b128 v[156:159], v69 offset:1952
	ds_read_b128 v[160:163], v69 offset:1984
	ds_read_b128 v[164:167], v69 offset:2016
	s_waitcnt lgkmcnt(8)
	s_waitcnt vmcnt(15)
	v_mfma_f32_32x32x16_bf16 v[2:17], v[104:107], v[72:75], v[2:17]
	s_waitcnt vmcnt(14)
	v_mfma_f32_32x32x16_bf16 v[2:17], v[108:111], v[76:79], v[2:17]
	s_waitcnt vmcnt(13)
	v_mfma_f32_32x32x16_bf16 v[2:17], v[112:115], v[80:83], v[2:17]
	s_waitcnt vmcnt(12)
	v_mfma_f32_32x32x16_bf16 v[2:17], v[116:119], v[84:87], v[2:17]
	s_waitcnt vmcnt(11)
	v_mfma_f32_32x32x16_bf16 v[2:17], v[120:123], v[88:91], v[2:17]
	s_waitcnt vmcnt(10)
	v_mfma_f32_32x32x16_bf16 v[2:17], v[124:127], v[92:95], v[2:17]
	s_waitcnt vmcnt(9)
	v_mfma_f32_32x32x16_bf16 v[2:17], v[128:131], v[96:99], v[2:17]
	s_waitcnt vmcnt(8)
	v_mfma_f32_32x32x16_bf16 v[2:17], v[132:135], v[100:103], v[2:17]
	global_load_dwordx4 v[72:75], v[70:71], off offset:1920
	global_load_dwordx4 v[76:79], v[70:71], off offset:1952
	global_load_dwordx4 v[80:83], v[70:71], off offset:1984
	global_load_dwordx4 v[84:87], v[70:71], off offset:2016
	global_load_dwordx4 v[88:91], v[70:71], off offset:2048
	global_load_dwordx4 v[92:95], v[70:71], off offset:2080
	global_load_dwordx4 v[96:99], v[70:71], off offset:2112
	global_load_dwordx4 v[100:103], v[70:71], off offset:2144
	ds_read_b128 v[104:107], v69 offset:2048
	ds_read_b128 v[108:111], v69 offset:2080
	ds_read_b128 v[112:115], v69 offset:2112
	ds_read_b128 v[116:119], v69 offset:2144
	ds_read_b128 v[120:123], v69 offset:2176
	ds_read_b128 v[124:127], v69 offset:2208
	ds_read_b128 v[128:131], v69 offset:2240
	ds_read_b128 v[132:135], v69 offset:2272
	s_waitcnt lgkmcnt(8)
	s_waitcnt vmcnt(15)
; #define LAS __attribute__((address_space(3)))
; __device__ __forceinline__ v16f mfma32(v8s a, v8s b, v16f c) { return __builtin_amdgcn_mfma_f32_32x32x16_bf16(a, b, c, 0, 0, 0); }
; __device__ __forceinline__ void compress_unit(LAS unsigned char* lds, int u, const bf16_t* QKV, const float* pe_k, const float* pe_v,
;                                               const bf16_t* CW1  , const bf16_t* CW2  , bf16_t* KCMP, bf16_t* VCMP) {
;     ...
;     for (int st = 0; st < 128; ++st) {
;         const int li = st >> 2, d0 = (st & 3) * 16;
;         const v4u ar = *(const v4u*)(Ag + (size_t)li * EVEN_PAD + d0);
;         const v4f pa = *(const LAS v4f*)(PE + li * 64 + d0 + hi * 8), pb = *(const LAS v4f*)(PE + li * 64 + d0 + hi * 8 + 4);
;         const v8s bfr = *(const v8s*)(Bg + st * 16);
;         v4u aw;
;         aw.x = pkbf(__uint_as_float(ar.x << 16) + pa.x, __uint_as_float(ar.x & 0xffff0000u) + pa.y);
;         aw.y = pkbf(__uint_as_float(ar.y << 16) + pa.z, __uint_as_float(ar.y & 0xffff0000u) + pa.w);
;         aw.z = pkbf(__uint_as_float(ar.z << 16) + pb.x, __uint_as_float(ar.z & 0xffff0000u) + pb.y);
;         aw.w = pkbf(__uint_as_float(ar.w << 16) + pb.z, __uint_as_float(ar.w & 0xffff0000u) + pb.w);
;         acc = mfma32(__builtin_bit_cast(v8s, aw), bfr, acc);
;     }
	v_mfma_f32_32x32x16_bf16 v[2:17], v[136:139], v[168:171], v[2:17]
	s_waitcnt vmcnt(14)
	v_mfma_f32_32x32x16_bf16 v[2:17], v[140:143], v[172:175], v[2:17]
	s_waitcnt vmcnt(13)
	v_mfma_f32_32x32x16_bf16 v[2:17], v[144:147], v[176:179], v[2:17]
	s_waitcnt vmcnt(12)
	v_mfma_f32_32x32x16_bf16 v[2:17], v[148:151], v[180:183], v[2:17]
	s_waitcnt vmcnt(11)
	v_mfma_f32_32x32x16_bf16 v[2:17], v[152:155], v[184:187], v[2:17]
	s_waitcnt vmcnt(10)
	v_mfma_f32_32x32x16_bf16 v[2:17], v[156:159], v[188:191], v[2:17]
	s_waitcnt vmcnt(9)
	v_mfma_f32_32x32x16_bf16 v[2:17], v[160:163], v[192:195], v[2:17]
	s_waitcnt vmcnt(8)
	v_mfma_f32_32x32x16_bf16 v[2:17], v[164:167], v[196:199], v[2:17]
	global_load_dwordx4 v[168:171], v[70:71], off offset:2176
	global_load_dwordx4 v[172:175], v[70:71], off offset:2208
	global_load_dwordx4 v[176:179], v[70:71], off offset:2240
	global_load_dwordx4 v[180:183], v[70:71], off offset:2272
	global_load_dwordx4 v[184:187], v[70:71], off offset:2304
	global_load_dwordx4 v[188:191], v[70:71], off offset:2336
	global_load_dwordx4 v[192:195], v[70:71], off offset:2368
	global_load_dwordx4 v[196:199], v[70:71], off offset:2400
	ds_read_b128 v[136:139], v69 offset:2304
	ds_read_b128 v[140:143], v69 offset:2336
	ds_read_b128 v[144:147], v69 offset:2368
	ds_read_b128 v[148:151], v69 offset:2400
	ds_read_b128 v[152:155], v69 offset:2432
	ds_read_b128 v[156:159], v69 offset:2464
	ds_read_b128 v[160:163], v69 offset:2496
	ds_read_b128 v[164:167], v69 offset:2528
	s_waitcnt lgkmcnt(8)
	s_waitcnt vmcnt(15)
	v_mfma_f32_32x32x16_bf16 v[2:17], v[104:107], v[72:75], v[2:17]
	s_waitcnt vmcnt(14)
	v_mfma_f32_32x32x16_bf16 v[2:17], v[108:111], v[76:79], v[2:17]
	s_waitcnt vmcnt(13)
	v_mfma_f32_32x32x16_bf16 v[2:17], v[112:115], v[80:83], v[2:17]
	s_waitcnt vmcnt(12)
	v_mfma_f32_32x32x16_bf16 v[2:17], v[116:119], v[84:87], v[2:17]
	s_waitcnt vmcnt(11)
	v_mfma_f32_32x32x16_bf16 v[2:17], v[120:123], v[88:91], v[2:17]
	s_waitcnt vmcnt(10)
	v_mfma_f32_32x32x16_bf16 v[2:17], v[124:127], v[92:95], v[2:17]
	s_waitcnt vmcnt(9)
	v_mfma_f32_32x32x16_bf16 v[2:17], v[128:131], v[96:99], v[2:17]
	s_waitcnt vmcnt(8)
	v_mfma_f32_32x32x16_bf16 v[2:17], v[132:135], v[100:103], v[2:17]
	global_load_dwordx4 v[72:75], v[70:71], off offset:2432
	global_load_dwordx4 v[76:79], v[70:71], off offset:2464
	global_load_dwordx4 v[80:83], v[70:71], off offset:2496
	global_load_dwordx4 v[84:87], v[70:71], off offset:2528
	global_load_dwordx4 v[88:91], v[70:71], off offset:2560
	global_load_dwordx4 v[92:95], v[70:71], off offset:2592
	global_load_dwordx4 v[96:99], v[70:71], off offset:2624
	global_load_dwordx4 v[100:103], v[70:71], off offset:2656
	ds_read_b128 v[104:107], v69 offset:2560
	ds_read_b128 v[108:111], v69 offset:2592
	ds_read_b128 v[112:115], v69 offset:2624
	ds_read_b128 v[116:119], v69 offset:2656
	ds_read_b128 v[120:123], v69 offset:2688
	ds_read_b128 v[124:127], v69 offset:2720
	ds_read_b128 v[128:131], v69 offset:2752
	ds_read_b128 v[132:135], v69 offset:2784
	s_waitcnt lgkmcnt(8)
	s_waitcnt vmcnt(15)
	v_mfma_f32_32x32x16_bf16 v[2:17], v[136:139], v[168:171], v[2:17]
	s_waitcnt vmcnt(14)
	v_mfma_f32_32x32x16_bf16 v[2:17], v[140:143], v[172:175], v[2:17]
	s_waitcnt vmcnt(13)
	v_mfma_f32_32x32x16_bf16 v[2:17], v[144:147], v[176:179], v[2:17]
	s_waitcnt vmcnt(12)
	v_mfma_f32_32x32x16_bf16 v[2:17], v[148:151], v[180:183], v[2:17]
	s_waitcnt vmcnt(11)
	v_mfma_f32_32x32x16_bf16 v[2:17], v[152:155], v[184:187], v[2:17]
	s_waitcnt vmcnt(10)
	v_mfma_f32_32x32x16_bf16 v[2:17], v[156:159], v[188:191], v[2:17]
	s_waitcnt vmcnt(9)
	v_mfma_f32_32x32x16_bf16 v[2:17], v[160:163], v[192:195], v[2:17]
	s_waitcnt vmcnt(8)
	v_mfma_f32_32x32x16_bf16 v[2:17], v[164:167], v[196:199], v[2:17]
	global_load_dwordx4 v[168:171], v[70:71], off offset:2688
	global_load_dwordx4 v[172:175], v[70:71], off offset:2720
	global_load_dwordx4 v[176:179], v[70:71], off offset:2752
	global_load_dwordx4 v[180:183], v[70:71], off offset:2784
	global_load_dwordx4 v[184:187], v[70:71], off offset:2816
	global_load_dwordx4 v[188:191], v[70:71], off offset:2848
	global_load_dwordx4 v[192:195], v[70:71], off offset:2880
	global_load_dwordx4 v[196:199], v[70:71], off offset:2912
	ds_read_b128 v[136:139], v69 offset:2816
	ds_read_b128 v[140:143], v69 offset:2848
	ds_read_b128 v[144:147], v69 offset:2880
	ds_read_b128 v[148:151], v69 offset:2912
	ds_read_b128 v[152:155], v69 offset:2944
	ds_read_b128 v[156:159], v69 offset:2976
	ds_read_b128 v[160:163], v69 offset:3008
	ds_read_b128 v[164:167], v69 offset:3040
	s_waitcnt lgkmcnt(8)
	s_waitcnt vmcnt(15)
	v_mfma_f32_32x32x16_bf16 v[2:17], v[104:107], v[72:75], v[2:17]
	s_waitcnt vmcnt(14)
	v_mfma_f32_32x32x16_bf16 v[2:17], v[108:111], v[76:79], v[2:17]
	s_waitcnt vmcnt(13)
	v_mfma_f32_32x32x16_bf16 v[2:17], v[112:115], v[80:83], v[2:17]
	s_waitcnt vmcnt(12)
	v_mfma_f32_32x32x16_bf16 v[2:17], v[116:119], v[84:87], v[2:17]
	s_waitcnt vmcnt(11)
	v_mfma_f32_32x32x16_bf16 v[2:17], v[120:123], v[88:91], v[2:17]
	s_waitcnt vmcnt(10)
	v_mfma_f32_32x32x16_bf16 v[2:17], v[124:127], v[92:95], v[2:17]
	s_waitcnt vmcnt(9)
	v_mfma_f32_32x32x16_bf16 v[2:17], v[128:131], v[96:99], v[2:17]
	s_waitcnt vmcnt(8)
	v_mfma_f32_32x32x16_bf16 v[2:17], v[132:135], v[100:103], v[2:17]
	global_load_dwordx4 v[72:75], v[70:71], off offset:2944
	global_load_dwordx4 v[76:79], v[70:71], off offset:2976
	global_load_dwordx4 v[80:83], v[70:71], off offset:3008
	global_load_dwordx4 v[84:87], v[70:71], off offset:3040
	global_load_dwordx4 v[88:91], v[70:71], off offset:3072
	global_load_dwordx4 v[92:95], v[70:71], off offset:3104
	global_load_dwordx4 v[96:99], v[70:71], off offset:3136
	global_load_dwordx4 v[100:103], v[70:71], off offset:3168
	ds_read_b128 v[104:107], v69 offset:3072
	ds_read_b128 v[108:111], v69 offset:3104
	ds_read_b128 v[112:115], v69 offset:3136
	ds_read_b128 v[116:119], v69 offset:3168
	ds_read_b128 v[120:123], v69 offset:3200
	ds_read_b128 v[124:127], v69 offset:3232
	ds_read_b128 v[128:131], v69 offset:3264
	ds_read_b128 v[132:135], v69 offset:3296
	s_waitcnt lgkmcnt(8)
; #define LAS __attribute__((address_space(3)))
; __device__ __forceinline__ v16f mfma32(v8s a, v8s b, v16f c) { return __builtin_amdgcn_mfma_f32_32x32x16_bf16(a, b, c, 0, 0, 0); }
; __device__ __forceinline__ void compress_unit(LAS unsigned char* lds, int u, const bf16_t* QKV, const float* pe_k, const float* pe_v,
;                                               const bf16_t* CW1  , const bf16_t* CW2  , bf16_t* KCMP, bf16_t* VCMP) {
;     ...
;     for (int st = 0; st < 128; ++st) {
;         const int li = st >> 2, d0 = (st & 3) * 16;
;         const v4u ar = *(const v4u*)(Ag + (size_t)li * EVEN_PAD + d0);
;         const v4f pa = *(const LAS v4f*)(PE + li * 64 + d0 + hi * 8), pb = *(const LAS v4f*)(PE + li * 64 + d0 + hi * 8 + 4);
;         const v8s bfr = *(const v8s*)(Bg + st * 16);
;         v4u aw;
;         aw.x = pkbf(__uint_as_float(ar.x << 16) + pa.x, __uint_as_float(ar.x & 0xffff0000u) + pa.y);
;         aw.y = pkbf(__uint_as_float(ar.y << 16) + pa.z, __uint_as_float(ar.y & 0xffff0000u) + pa.w);
;         aw.z = pkbf(__uint_as_float(ar.z << 16) + pb.x, __uint_as_float(ar.z & 0xffff0000u) + pb.y);
;         aw.w = pkbf(__uint_as_float(ar.w << 16) + pb.z, __uint_as_float(ar.w & 0xffff0000u) + pb.w);
;         acc = mfma32(__builtin_bit_cast(v8s, aw), bfr, acc);
;     }
	s_waitcnt vmcnt(15)
	v_mfma_f32_32x32x16_bf16 v[2:17], v[136:139], v[168:171], v[2:17]
	s_waitcnt vmcnt(14)
	v_mfma_f32_32x32x16_bf16 v[2:17], v[140:143], v[172:175], v[2:17]
	s_waitcnt vmcnt(13)
	v_mfma_f32_32x32x16_bf16 v[2:17], v[144:147], v[176:179], v[2:17]
	s_waitcnt vmcnt(12)
	v_mfma_f32_32x32x16_bf16 v[2:17], v[148:151], v[180:183], v[2:17]
	s_waitcnt vmcnt(11)
	v_mfma_f32_32x32x16_bf16 v[2:17], v[152:155], v[184:187], v[2:17]
	s_waitcnt vmcnt(10)
	v_mfma_f32_32x32x16_bf16 v[2:17], v[156:159], v[188:191], v[2:17]
	s_waitcnt vmcnt(9)
	v_mfma_f32_32x32x16_bf16 v[2:17], v[160:163], v[192:195], v[2:17]
	s_waitcnt vmcnt(8)
	v_mfma_f32_32x32x16_bf16 v[2:17], v[164:167], v[196:199], v[2:17]
	global_load_dwordx4 v[168:171], v[70:71], off offset:3200
	global_load_dwordx4 v[172:175], v[70:71], off offset:3232
	global_load_dwordx4 v[176:179], v[70:71], off offset:3264
	global_load_dwordx4 v[180:183], v[70:71], off offset:3296
	global_load_dwordx4 v[184:187], v[70:71], off offset:3328
	global_load_dwordx4 v[188:191], v[70:71], off offset:3360
	global_load_dwordx4 v[192:195], v[70:71], off offset:3392
	global_load_dwordx4 v[196:199], v[70:71], off offset:3424
	ds_read_b128 v[136:139], v69 offset:3328
	ds_read_b128 v[140:143], v69 offset:3360
	ds_read_b128 v[144:147], v69 offset:3392
	ds_read_b128 v[148:151], v69 offset:3424
	ds_read_b128 v[152:155], v69 offset:3456
	ds_read_b128 v[156:159], v69 offset:3488
	ds_read_b128 v[160:163], v69 offset:3520
	ds_read_b128 v[164:167], v69 offset:3552
	s_waitcnt lgkmcnt(8)
	s_waitcnt vmcnt(15)
	v_mfma_f32_32x32x16_bf16 v[2:17], v[104:107], v[72:75], v[2:17]
	s_waitcnt vmcnt(14)
	v_mfma_f32_32x32x16_bf16 v[2:17], v[108:111], v[76:79], v[2:17]
	s_waitcnt vmcnt(13)
	v_mfma_f32_32x32x16_bf16 v[2:17], v[112:115], v[80:83], v[2:17]
	s_waitcnt vmcnt(12)
	v_mfma_f32_32x32x16_bf16 v[2:17], v[116:119], v[84:87], v[2:17]
	s_waitcnt vmcnt(11)
	v_mfma_f32_32x32x16_bf16 v[2:17], v[120:123], v[88:91], v[2:17]
	s_waitcnt vmcnt(10)
	v_mfma_f32_32x32x16_bf16 v[2:17], v[124:127], v[92:95], v[2:17]
	s_waitcnt vmcnt(9)
	v_mfma_f32_32x32x16_bf16 v[2:17], v[128:131], v[96:99], v[2:17]
	s_waitcnt vmcnt(8)
	v_mfma_f32_32x32x16_bf16 v[2:17], v[132:135], v[100:103], v[2:17]
	global_load_dwordx4 v[72:75], v[70:71], off offset:3456
	global_load_dwordx4 v[76:79], v[70:71], off offset:3488
	global_load_dwordx4 v[80:83], v[70:71], off offset:3520
	global_load_dwordx4 v[84:87], v[70:71], off offset:3552
	global_load_dwordx4 v[88:91], v[70:71], off offset:3584
	global_load_dwordx4 v[92:95], v[70:71], off offset:3616
	global_load_dwordx4 v[96:99], v[70:71], off offset:3648
	global_load_dwordx4 v[100:103], v[70:71], off offset:3680
	ds_read_b128 v[104:107], v69 offset:3584
	ds_read_b128 v[108:111], v69 offset:3616
	ds_read_b128 v[112:115], v69 offset:3648
	ds_read_b128 v[116:119], v69 offset:3680
	ds_read_b128 v[120:123], v69 offset:3712
	ds_read_b128 v[124:127], v69 offset:3744
	ds_read_b128 v[128:131], v69 offset:3776
	ds_read_b128 v[132:135], v69 offset:3808
	s_waitcnt lgkmcnt(8)
	s_waitcnt vmcnt(15)
	v_mfma_f32_32x32x16_bf16 v[2:17], v[136:139], v[168:171], v[2:17]
	s_waitcnt vmcnt(14)
	v_mfma_f32_32x32x16_bf16 v[2:17], v[140:143], v[172:175], v[2:17]
	s_waitcnt vmcnt(13)
	v_mfma_f32_32x32x16_bf16 v[2:17], v[144:147], v[176:179], v[2:17]
	s_waitcnt vmcnt(12)
	v_mfma_f32_32x32x16_bf16 v[2:17], v[148:151], v[180:183], v[2:17]
	s_waitcnt vmcnt(11)
	v_mfma_f32_32x32x16_bf16 v[2:17], v[152:155], v[184:187], v[2:17]
	s_waitcnt vmcnt(10)
	v_mfma_f32_32x32x16_bf16 v[2:17], v[156:159], v[188:191], v[2:17]
	s_waitcnt vmcnt(9)
	v_mfma_f32_32x32x16_bf16 v[2:17], v[160:163], v[192:195], v[2:17]
	s_waitcnt vmcnt(8)
	v_mfma_f32_32x32x16_bf16 v[2:17], v[164:167], v[196:199], v[2:17]
	global_load_dwordx4 v[168:171], v[70:71], off offset:3712
	global_load_dwordx4 v[172:175], v[70:71], off offset:3744
	global_load_dwordx4 v[176:179], v[70:71], off offset:3776
	global_load_dwordx4 v[180:183], v[70:71], off offset:3808
	global_load_dwordx4 v[184:187], v[70:71], off offset:3840
	global_load_dwordx4 v[188:191], v[70:71], off offset:3872
	global_load_dwordx4 v[192:195], v[70:71], off offset:3904
	global_load_dwordx4 v[196:199], v[70:71], off offset:3936
	ds_read_b128 v[136:139], v69 offset:3840
	ds_read_b128 v[140:143], v69 offset:3872
	ds_read_b128 v[144:147], v69 offset:3904
	ds_read_b128 v[148:151], v69 offset:3936
	ds_read_b128 v[152:155], v69 offset:3968
	ds_read_b128 v[156:159], v69 offset:4000
	ds_read_b128 v[160:163], v69 offset:4032
	ds_read_b128 v[164:167], v69 offset:4064
	s_waitcnt lgkmcnt(8)
	s_waitcnt vmcnt(15)
	v_mfma_f32_32x32x16_bf16 v[2:17], v[104:107], v[72:75], v[2:17]
	s_waitcnt vmcnt(14)
	v_mfma_f32_32x32x16_bf16 v[2:17], v[108:111], v[76:79], v[2:17]
	s_waitcnt vmcnt(13)
	v_mfma_f32_32x32x16_bf16 v[2:17], v[112:115], v[80:83], v[2:17]
	s_waitcnt vmcnt(12)
	v_mfma_f32_32x32x16_bf16 v[2:17], v[116:119], v[84:87], v[2:17]
	s_waitcnt vmcnt(11)
	v_mfma_f32_32x32x16_bf16 v[2:17], v[120:123], v[88:91], v[2:17]
	s_waitcnt vmcnt(10)
	v_mfma_f32_32x32x16_bf16 v[2:17], v[124:127], v[92:95], v[2:17]
	s_waitcnt vmcnt(9)
	v_mfma_f32_32x32x16_bf16 v[2:17], v[128:131], v[96:99], v[2:17]
	s_waitcnt vmcnt(8)
	v_mfma_f32_32x32x16_bf16 v[2:17], v[132:135], v[100:103], v[2:17]
	s_waitcnt lgkmcnt(0)
	s_waitcnt vmcnt(7)
	v_mfma_f32_32x32x16_bf16 v[2:17], v[136:139], v[168:171], v[2:17]
	s_waitcnt vmcnt(6)
	v_mfma_f32_32x32x16_bf16 v[2:17], v[140:143], v[172:175], v[2:17]
	s_waitcnt vmcnt(5)
	v_mfma_f32_32x32x16_bf16 v[2:17], v[144:147], v[176:179], v[2:17]
	s_waitcnt vmcnt(4)
	v_mfma_f32_32x32x16_bf16 v[2:17], v[148:151], v[180:183], v[2:17]
	s_waitcnt vmcnt(3)
; __device__ __forceinline__ int crow(int r, int hi) { return (r & 3) + 8 * (r >> 2) + 4 * hi; }
; __device__ __forceinline__ v16f mfma32(v8s a, v8s b, v16f c) { return __builtin_amdgcn_mfma_f32_32x32x16_bf16(a, b, c, 0, 0, 0); }
; __device__ __forceinline__ float gelu_tanh(float x) {
;     const float u = 0.7978845608028654f * (x + 0.044715f * x * x * x);
;     const float t = 1.f - 2.f / (1.f + __expf(2.f * u));
;     return 0.5f * x * (1.f + t);
; }
; __device__ __forceinline__ void compress_unit(LAS unsigned char* lds, int u, const bf16_t* QKV, const float* pe_k, const float* pe_v,
;                                               const bf16_t* CW1  , const bf16_t* CW2  , bf16_t* KCMP, bf16_t* VCMP) {
;     ...
;         acc = mfma32(__builtin_bit_cast(v8s, aw), bfr, acc);
;     }
; #pragma unroll
;     for (int r = 0; r < 16; ++r) HID[crow(r, hi) * 264 + 32 * w + r32] = (bf16_t)(pkbf(gelu_tanh(acc[r]), 0.f) & 0xffffu);
	v_mfma_f32_32x32x16_bf16 v[2:17], v[152:155], v[184:187], v[2:17]
	s_waitcnt vmcnt(2)
	v_mfma_f32_32x32x16_bf16 v[2:17], v[156:159], v[188:191], v[2:17]
	s_waitcnt vmcnt(1)
	v_mfma_f32_32x32x16_bf16 v[2:17], v[160:163], v[192:195], v[2:17]
	s_waitcnt vmcnt(0)
	v_mfma_f32_32x32x16_bf16 v[2:17], v[164:167], v[196:199], v[2:17]
	s_nop 10
	v_mul_f32_e32 v18, 0x3d372713, v2
	v_mul_f32_e32 v18, v2, v18
	v_fma_f32 v18, v2, v18, v2
	v_mul_f32_e32 v18, 0x3f4c422a, v18
	v_add_f32_e32 v18, v18, v18
	v_mul_f32_e32 v18, 0x3fb8aa3b, v18
	v_exp_f32_e32 v19, v18
	v_mul_f32_e32 v2, 0.5, v2
	v_lshlrev_b32_e32 v18, 2, v40
	v_add_f32_e32 v19, 1.0, v19
	v_div_scale_f32 v20, s[16:17], v19, v19, 2.0
	v_rcp_f32_e32 v21, v20
	s_lshl_b32 s16, s10, 1
	s_add_i32 s16, s16, 0
	v_lshl_add_u32 v22, v41, 1, s16
	v_fma_f32 v23, -v20, v21, 1.0
	v_fmac_f32_e32 v21, v23, v21
	v_div_scale_f32 v23, vcc, 2.0, v19, 2.0
	v_mul_f32_e32 v24, v23, v21
	v_fma_f32 v25, -v20, v24, v23
	v_fmac_f32_e32 v24, v25, v21
	v_fma_f32 v20, -v20, v24, v23
	v_div_fmas_f32 v20, v20, v21, v24
	v_div_fixup_f32 v19, v20, v19, 2.0
	v_mul_f32_e32 v20, 0x3d372713, v3
	v_mul_f32_e32 v20, v3, v20
	v_fma_f32 v20, v3, v20, v3
	v_mul_f32_e32 v20, 0x3f4c422a, v20
	v_add_f32_e32 v20, v20, v20
	v_mul_f32_e32 v20, 0x3fb8aa3b, v20
	v_exp_f32_e32 v20, v20
	v_sub_f32_e32 v19, 1.0, v19
	v_add_f32_e32 v19, 1.0, v19
	v_mul_f32_e32 v2, v2, v19
	v_add_f32_e32 v19, 1.0, v20
	v_div_scale_f32 v20, s[16:17], v19, v19, 2.0
	v_rcp_f32_e32 v21, v20
	s_movk_i32 s16, 0x840
	v_cvt_pk_bf16_f32 v2, v2, s0
	v_mad_u32_u24 v23, v40, s16, v22
	ds_write_b16 v23, v2
	v_fma_f32 v2, -v20, v21, 1.0
	v_fmac_f32_e32 v21, v2, v21
	v_div_scale_f32 v2, vcc, 2.0, v19, 2.0
	v_mul_f32_e32 v23, v2, v21
	v_fma_f32 v24, -v20, v23, v2
	v_fmac_f32_e32 v23, v24, v21
	v_fma_f32 v2, -v20, v23, v2
	v_div_fmas_f32 v2, v2, v21, v23
	v_div_fixup_f32 v2, v2, v19, 2.0
	v_mul_f32_e32 v19, 0x3d372713, v4
	v_mul_f32_e32 v19, v4, v19
	v_fma_f32 v19, v4, v19, v4
	v_mul_f32_e32 v19, 0x3f4c422a, v19
	v_add_f32_e32 v19, v19, v19
	v_mul_f32_e32 v19, 0x3fb8aa3b, v19
	v_exp_f32_e32 v19, v19
	v_sub_f32_e32 v2, 1.0, v2
	v_mul_f32_e32 v3, 0.5, v3
	v_add_f32_e32 v2, 1.0, v2
	v_mul_f32_e32 v2, v3, v2
	v_add_f32_e32 v3, 1.0, v19
	v_div_scale_f32 v19, s[16:17], v3, v3, 2.0
	v_rcp_f32_e32 v20, v19
	v_or_b32_e32 v21, 1, v18
	s_movk_i32 s16, 0x210
	v_cvt_pk_bf16_f32 v2, v2, s0
	v_mad_u32_u24 v22, v21, s16, v22
	ds_write_b16 v22, v2
	v_fma_f32 v2, -v19, v20, 1.0
	v_fmac_f32_e32 v20, v2, v20
	v_div_scale_f32 v2, vcc, 2.0, v3, 2.0
	v_mul_f32_e32 v23, v2, v20
	v_fma_f32 v24, -v19, v23, v2
	v_fmac_f32_e32 v23, v24, v20
	v_fma_f32 v2, -v19, v23, v2
	v_div_fmas_f32 v2, v2, v20, v23
	v_div_fixup_f32 v2, v2, v3, 2.0
	v_mul_f32_e32 v3, 0x3d372713, v5
	v_mul_f32_e32 v3, v5, v3
	v_fma_f32 v3, v5, v3, v5
	v_mul_f32_e32 v3, 0x3f4c422a, v3
	v_add_f32_e32 v3, v3, v3
	v_mul_f32_e32 v3, 0x3fb8aa3b, v3
	v_exp_f32_e32 v3, v3
	v_sub_f32_e32 v2, 1.0, v2
	v_mul_f32_e32 v4, 0.5, v4
	v_add_f32_e32 v2, 1.0, v2
	v_add_f32_e32 v3, 1.0, v3
	v_div_scale_f32 v19, s[16:17], v3, v3, 2.0
	v_rcp_f32_e32 v20, v19
	v_mul_f32_e32 v2, v4, v2
	v_cvt_pk_bf16_f32 v2, v2, s0
	ds_write_b16 v22, v2 offset:528
	v_fma_f32 v2, -v19, v20, 1.0
	v_fmac_f32_e32 v20, v2, v20
	v_div_scale_f32 v2, vcc, 2.0, v3, 2.0
	v_mul_f32_e32 v4, v2, v20
	v_fma_f32 v23, -v19, v4, v2
	v_fmac_f32_e32 v4, v23, v20
	v_fma_f32 v2, -v19, v4, v2
	v_div_fmas_f32 v2, v2, v20, v4
	v_div_fixup_f32 v2, v2, v3, 2.0
	v_mul_f32_e32 v3, 0x3d372713, v6
	v_mul_f32_e32 v3, v6, v3
	v_fma_f32 v3, v6, v3, v6
	v_mul_f32_e32 v3, 0x3f4c422a, v3
	v_add_f32_e32 v3, v3, v3
	v_mul_f32_e32 v3, 0x3fb8aa3b, v3
	v_exp_f32_e32 v3, v3
	v_mul_f32_e32 v4, 0.5, v5
	v_sub_f32_e32 v2, 1.0, v2
	v_add_f32_e32 v2, 1.0, v2
	v_add_f32_e32 v3, 1.0, v3
	v_div_scale_f32 v5, s[16:17], v3, v3, 2.0
	v_rcp_f32_e32 v19, v5
	v_mul_f32_e32 v2, v4, v2
	v_cvt_pk_bf16_f32 v2, v2, s0
	ds_write_b16 v22, v2 offset:1056
	v_fma_f32 v2, -v5, v19, 1.0
	v_fmac_f32_e32 v19, v2, v19
	v_div_scale_f32 v2, vcc, 2.0, v3, 2.0
	v_mul_f32_e32 v4, v2, v19
	v_fma_f32 v20, -v5, v4, v2
	v_fmac_f32_e32 v4, v20, v19
	v_fma_f32 v2, -v5, v4, v2
	v_div_fmas_f32 v2, v2, v19, v4
	v_div_fixup_f32 v2, v2, v3, 2.0
	v_mul_f32_e32 v3, 0x3d372713, v7
	v_mul_f32_e32 v3, v7, v3
	v_fma_f32 v3, v7, v3, v7
	v_mul_f32_e32 v3, 0x3f4c422a, v3
	v_add_f32_e32 v3, v3, v3
	v_mul_f32_e32 v3, 0x3fb8aa3b, v3
	v_exp_f32_e32 v3, v3
	v_sub_f32_e32 v2, 1.0, v2
	v_mul_f32_e32 v4, 0.5, v6
	v_add_f32_e32 v2, 1.0, v2
	v_add_f32_e32 v3, 1.0, v3
	v_div_scale_f32 v5, s[16:17], v3, v3, 2.0
	v_rcp_f32_e32 v6, v5
	v_mul_f32_e32 v2, v4, v2
	v_cvt_pk_bf16_f32 v2, v2, s0
	ds_write_b16 v22, v2 offset:3696
	v_fma_f32 v2, -v5, v6, 1.0
	v_fmac_f32_e32 v6, v2, v6
	v_div_scale_f32 v2, vcc, 2.0, v3, 2.0
	v_mul_f32_e32 v4, v2, v6
	v_fma_f32 v19, -v5, v4, v2
	v_fmac_f32_e32 v4, v19, v6
	v_fma_f32 v2, -v5, v4, v2
	v_div_fmas_f32 v2, v2, v6, v4
	v_div_fixup_f32 v2, v2, v3, 2.0
	v_mul_f32_e32 v3, 0x3d372713, v8
	v_mul_f32_e32 v3, v8, v3
	v_fma_f32 v3, v8, v3, v8
	v_mul_f32_e32 v3, 0x3f4c422a, v3
	v_add_f32_e32 v3, v3, v3
	v_mul_f32_e32 v3, 0x3fb8aa3b, v3
	v_exp_f32_e32 v3, v3
	v_sub_f32_e32 v2, 1.0, v2
	v_mul_f32_e32 v4, 0.5, v7
	v_add_f32_e32 v2, 1.0, v2
	v_add_f32_e32 v3, 1.0, v3
	v_div_scale_f32 v5, s[16:17], v3, v3, 2.0
	v_rcp_f32_e32 v6, v5
	v_mul_f32_e32 v2, v4, v2
	v_cvt_pk_bf16_f32 v2, v2, s0
	ds_write_b16 v22, v2 offset:4224
	v_fma_f32 v2, -v5, v6, 1.0
	v_fmac_f32_e32 v6, v2, v6
	v_div_scale_f32 v2, vcc, 2.0, v3, 2.0
	v_mul_f32_e32 v4, v2, v6
	v_fma_f32 v7, -v5, v4, v2
	v_fmac_f32_e32 v4, v7, v6
	v_fma_f32 v2, -v5, v4, v2
	v_div_fmas_f32 v2, v2, v6, v4
	v_div_fixup_f32 v2, v2, v3, 2.0
; __device__ __forceinline__ int crow(int r, int hi) { return (r & 3) + 8 * (r >> 2) + 4 * hi; }
; __device__ __forceinline__ float gelu_tanh(float x) {
;     const float u = 0.7978845608028654f * (x + 0.044715f * x * x * x);
;     const float t = 1.f - 2.f / (1.f + __expf(2.f * u));
;     return 0.5f * x * (1.f + t);
; }
; __device__ __forceinline__ void compress_unit(LAS unsigned char* lds, int u, const bf16_t* QKV, const float* pe_k, const float* pe_v,
;                                               const bf16_t* CW1  , const bf16_t* CW2  , bf16_t* KCMP, bf16_t* VCMP) {
;     ...
;     for (int r = 0; r < 16; ++r) HID[crow(r, hi) * 264 + 32 * w + r32] = (bf16_t)(pkbf(gelu_tanh(acc[r]), 0.f) & 0xffffu);
;     __syncthreads();
	v_mul_f32_e32 v3, 0x3d372713, v9
	v_mul_f32_e32 v3, v9, v3
	v_fma_f32 v3, v9, v3, v9
	v_mul_f32_e32 v3, 0x3f4c422a, v3
	v_add_f32_e32 v3, v3, v3
	v_mul_f32_e32 v3, 0x3fb8aa3b, v3
	v_exp_f32_e32 v3, v3
	v_sub_f32_e32 v2, 1.0, v2
	v_mul_f32_e32 v4, 0.5, v8
	v_add_f32_e32 v2, 1.0, v2
	v_add_f32_e32 v3, 1.0, v3
	v_div_scale_f32 v5, s[16:17], v3, v3, 2.0
	v_rcp_f32_e32 v6, v5
	v_mul_f32_e32 v2, v4, v2
	v_cvt_pk_bf16_f32 v2, v2, s0
	ds_write_b16 v22, v2 offset:4752
	v_fma_f32 v2, -v5, v6, 1.0
	v_fmac_f32_e32 v6, v2, v6
	v_div_scale_f32 v2, vcc, 2.0, v3, 2.0
	v_mul_f32_e32 v4, v2, v6
	v_fma_f32 v7, -v5, v4, v2
	v_fmac_f32_e32 v4, v7, v6
	v_fma_f32 v2, -v5, v4, v2
	v_div_fmas_f32 v2, v2, v6, v4
	v_div_fixup_f32 v2, v2, v3, 2.0
	v_mul_f32_e32 v3, 0x3d372713, v10
	v_mul_f32_e32 v3, v10, v3
	v_fma_f32 v3, v10, v3, v10
	v_mul_f32_e32 v3, 0x3f4c422a, v3
	v_add_f32_e32 v3, v3, v3
	v_mul_f32_e32 v3, 0x3fb8aa3b, v3
	v_exp_f32_e32 v3, v3
	v_sub_f32_e32 v2, 1.0, v2
	v_mul_f32_e32 v4, 0.5, v9
	v_add_f32_e32 v2, 1.0, v2
	v_add_f32_e32 v3, 1.0, v3
	v_div_scale_f32 v5, s[16:17], v3, v3, 2.0
	v_rcp_f32_e32 v6, v5
	v_mul_f32_e32 v2, v4, v2
	v_cvt_pk_bf16_f32 v2, v2, s0
	ds_write_b16 v22, v2 offset:5280
	v_fma_f32 v2, -v5, v6, 1.0
	v_fmac_f32_e32 v6, v2, v6
	v_div_scale_f32 v2, vcc, 2.0, v3, 2.0
	v_mul_f32_e32 v4, v2, v6
	v_fma_f32 v7, -v5, v4, v2
	v_fmac_f32_e32 v4, v7, v6
	v_fma_f32 v2, -v5, v4, v2
	v_div_fmas_f32 v2, v2, v6, v4
	v_div_fixup_f32 v2, v2, v3, 2.0
	v_mul_f32_e32 v3, 0x3d372713, v11
	v_mul_f32_e32 v3, v11, v3
	v_fma_f32 v3, v11, v3, v11
	v_mul_f32_e32 v3, 0x3f4c422a, v3
	v_add_f32_e32 v3, v3, v3
	v_mul_f32_e32 v3, 0x3fb8aa3b, v3
	v_exp_f32_e32 v3, v3
	v_sub_f32_e32 v2, 1.0, v2
	v_mul_f32_e32 v4, 0.5, v10
	v_add_f32_e32 v2, 1.0, v2
	v_add_f32_e32 v3, 1.0, v3
	v_div_scale_f32 v5, s[16:17], v3, v3, 2.0
	v_rcp_f32_e32 v6, v5
	v_mul_f32_e32 v2, v4, v2
	v_cvt_pk_bf16_f32 v2, v2, s0
	ds_write_b16 v22, v2 offset:7920
	v_fma_f32 v2, -v5, v6, 1.0
	v_fmac_f32_e32 v6, v2, v6
	v_div_scale_f32 v2, vcc, 2.0, v3, 2.0
	v_mul_f32_e32 v4, v2, v6
	v_fma_f32 v7, -v5, v4, v2
	v_fmac_f32_e32 v4, v7, v6
	v_fma_f32 v2, -v5, v4, v2
	v_div_fmas_f32 v2, v2, v6, v4
	v_div_fixup_f32 v2, v2, v3, 2.0
	v_mul_f32_e32 v3, 0x3d372713, v12
	v_mul_f32_e32 v3, v12, v3
	v_fma_f32 v3, v12, v3, v12
	v_mul_f32_e32 v3, 0x3f4c422a, v3
	v_add_f32_e32 v3, v3, v3
	v_mul_f32_e32 v3, 0x3fb8aa3b, v3
	v_exp_f32_e32 v3, v3
	v_sub_f32_e32 v2, 1.0, v2
	v_mul_f32_e32 v4, 0.5, v11
	v_add_f32_e32 v2, 1.0, v2
	v_add_f32_e32 v3, 1.0, v3
	v_div_scale_f32 v5, s[16:17], v3, v3, 2.0
	v_rcp_f32_e32 v6, v5
	v_mul_f32_e32 v2, v4, v2
	v_cvt_pk_bf16_f32 v2, v2, s0
	ds_write_b16 v22, v2 offset:8448
	v_fma_f32 v2, -v5, v6, 1.0
	v_fmac_f32_e32 v6, v2, v6
	v_div_scale_f32 v2, vcc, 2.0, v3, 2.0
	v_mul_f32_e32 v4, v2, v6
	v_fma_f32 v7, -v5, v4, v2
	v_fmac_f32_e32 v4, v7, v6
	v_fma_f32 v2, -v5, v4, v2
	v_div_fmas_f32 v2, v2, v6, v4
	v_div_fixup_f32 v2, v2, v3, 2.0
	v_mul_f32_e32 v3, 0x3d372713, v13
	v_mul_f32_e32 v3, v13, v3
	v_fma_f32 v3, v13, v3, v13
	v_mul_f32_e32 v3, 0x3f4c422a, v3
	v_add_f32_e32 v3, v3, v3
	v_mul_f32_e32 v3, 0x3fb8aa3b, v3
	v_exp_f32_e32 v3, v3
	v_sub_f32_e32 v2, 1.0, v2
	v_mul_f32_e32 v4, 0.5, v12
	v_add_f32_e32 v2, 1.0, v2
	v_add_f32_e32 v3, 1.0, v3
	v_div_scale_f32 v5, s[16:17], v3, v3, 2.0
	v_rcp_f32_e32 v6, v5
	v_mul_f32_e32 v2, v4, v2
	v_cvt_pk_bf16_f32 v2, v2, s0
	ds_write_b16 v22, v2 offset:8976
	v_fma_f32 v2, -v5, v6, 1.0
	v_fmac_f32_e32 v6, v2, v6
	v_div_scale_f32 v2, vcc, 2.0, v3, 2.0
	v_mul_f32_e32 v4, v2, v6
	v_fma_f32 v7, -v5, v4, v2
	v_fmac_f32_e32 v4, v7, v6
	v_fma_f32 v2, -v5, v4, v2
	v_div_fmas_f32 v2, v2, v6, v4
	v_div_fixup_f32 v2, v2, v3, 2.0
	v_mul_f32_e32 v3, 0x3d372713, v14
	v_mul_f32_e32 v3, v14, v3
	v_fma_f32 v3, v14, v3, v14
	v_mul_f32_e32 v3, 0x3f4c422a, v3
	v_add_f32_e32 v3, v3, v3
	v_mul_f32_e32 v3, 0x3fb8aa3b, v3
	v_exp_f32_e32 v3, v3
	v_sub_f32_e32 v2, 1.0, v2
	v_mul_f32_e32 v4, 0.5, v13
	v_add_f32_e32 v2, 1.0, v2
	v_add_f32_e32 v3, 1.0, v3
	v_div_scale_f32 v5, s[16:17], v3, v3, 2.0
	v_rcp_f32_e32 v6, v5
	v_mul_f32_e32 v2, v4, v2
	v_cvt_pk_bf16_f32 v2, v2, s0
	ds_write_b16 v22, v2 offset:9504
	v_fma_f32 v2, -v5, v6, 1.0
	v_fmac_f32_e32 v6, v2, v6
	v_div_scale_f32 v2, vcc, 2.0, v3, 2.0
	v_mul_f32_e32 v4, v2, v6
	v_fma_f32 v7, -v5, v4, v2
	v_fmac_f32_e32 v4, v7, v6
	v_fma_f32 v2, -v5, v4, v2
	v_div_fmas_f32 v2, v2, v6, v4
	v_div_fixup_f32 v2, v2, v3, 2.0
	v_mul_f32_e32 v3, 0x3d372713, v15
	v_mul_f32_e32 v3, v15, v3
	v_fma_f32 v3, v15, v3, v15
	v_mul_f32_e32 v3, 0x3f4c422a, v3
	v_add_f32_e32 v3, v3, v3
	v_mul_f32_e32 v3, 0x3fb8aa3b, v3
	v_exp_f32_e32 v3, v3
	v_sub_f32_e32 v2, 1.0, v2
	v_mul_f32_e32 v4, 0.5, v14
	v_add_f32_e32 v2, 1.0, v2
	v_add_f32_e32 v3, 1.0, v3
	v_div_scale_f32 v5, s[16:17], v3, v3, 2.0
	v_rcp_f32_e32 v6, v5
	v_mul_f32_e32 v2, v4, v2
	v_cvt_pk_bf16_f32 v2, v2, s0
	ds_write_b16 v22, v2 offset:12144
	v_fma_f32 v2, -v5, v6, 1.0
	v_fmac_f32_e32 v6, v2, v6
	v_div_scale_f32 v2, vcc, 2.0, v3, 2.0
	v_mul_f32_e32 v4, v2, v6
	v_fma_f32 v7, -v5, v4, v2
	v_fmac_f32_e32 v4, v7, v6
	v_fma_f32 v2, -v5, v4, v2
	v_div_fmas_f32 v2, v2, v6, v4
	v_div_fixup_f32 v2, v2, v3, 2.0
	v_mul_f32_e32 v3, 0x3d372713, v16
	v_mul_f32_e32 v3, v16, v3
	v_fma_f32 v3, v16, v3, v16
	v_mul_f32_e32 v3, 0x3f4c422a, v3
	v_add_f32_e32 v3, v3, v3
	v_mul_f32_e32 v3, 0x3fb8aa3b, v3
	v_exp_f32_e32 v3, v3
	v_sub_f32_e32 v2, 1.0, v2
	v_mul_f32_e32 v4, 0.5, v15
	v_add_f32_e32 v2, 1.0, v2
	v_add_f32_e32 v3, 1.0, v3
	v_div_scale_f32 v5, s[16:17], v3, v3, 2.0
	v_rcp_f32_e32 v6, v5
	v_mul_f32_e32 v2, v4, v2
	v_cvt_pk_bf16_f32 v2, v2, s0
	ds_write_b16 v22, v2 offset:12672
	v_fma_f32 v2, -v5, v6, 1.0
	v_fmac_f32_e32 v6, v2, v6
	v_div_scale_f32 v2, vcc, 2.0, v3, 2.0
	v_mul_f32_e32 v4, v2, v6
	v_fma_f32 v7, -v5, v4, v2
	v_fmac_f32_e32 v4, v7, v6
	v_fma_f32 v2, -v5, v4, v2
	v_div_fmas_f32 v2, v2, v6, v4
	v_div_fixup_f32 v2, v2, v3, 2.0
	v_mul_f32_e32 v3, 0x3d372713, v17
	v_mul_f32_e32 v3, v17, v3
	v_fma_f32 v3, v17, v3, v17
	v_mul_f32_e32 v3, 0x3f4c422a, v3
	v_add_f32_e32 v3, v3, v3
	v_mul_f32_e32 v3, 0x3fb8aa3b, v3
	v_exp_f32_e32 v3, v3
	v_sub_f32_e32 v2, 1.0, v2
	v_mul_f32_e32 v4, 0.5, v16
	v_add_f32_e32 v2, 1.0, v2
	v_add_f32_e32 v3, 1.0, v3
	v_div_scale_f32 v5, s[16:17], v3, v3, 2.0
	v_rcp_f32_e32 v6, v5
	v_mul_f32_e32 v2, v4, v2
	v_cvt_pk_bf16_f32 v2, v2, s0
	ds_write_b16 v22, v2 offset:13200
	v_fma_f32 v2, -v5, v6, 1.0
	v_fmac_f32_e32 v6, v2, v6
	v_div_scale_f32 v2, vcc, 2.0, v3, 2.0
	v_mul_f32_e32 v4, v2, v6
	v_fma_f32 v7, -v5, v4, v2
	v_fmac_f32_e32 v4, v7, v6
	v_fma_f32 v2, -v5, v4, v2
	v_div_fmas_f32 v2, v2, v6, v4
	v_div_fixup_f32 v2, v2, v3, 2.0
	v_sub_f32_e32 v2, 1.0, v2
	v_mul_f32_e32 v3, 0.5, v17
	v_add_f32_e32 v2, 1.0, v2
	v_mul_f32_e32 v2, v3, v2
	v_cvt_pk_bf16_f32 v2, v2, s0
	s_cmp_lt_i32 s29, 2
	ds_write_b16 v22, v2 offset:13728
	s_waitcnt lgkmcnt(0)
	s_barrier
; #define LAS __attribute__((address_space(3)))
; __device__ __forceinline__ int crow(int r, int hi) { return (r & 3) + 8 * (r >> 2) + 4 * hi; }
; __device__ __forceinline__ v16f mfma32(v8s a, v8s b, v16f c) { return __builtin_amdgcn_mfma_f32_32x32x16_bf16(a, b, c, 0, 0, 0); }
; __device__ __forceinline__ void compress_unit(LAS unsigned char* lds, int u, const bf16_t* QKV, const float* pe_k, const float* pe_v,
;                                               const bf16_t* CW1  , const bf16_t* CW2  , bf16_t* KCMP, bf16_t* VCMP) {
;     ...
;     if (w < 2) {
;         v16f o;
; #pragma unroll
;         for (int r = 0; r < 16; ++r) o[r] = 0.f;
;         const bf16_t* B2 = W2 + (size_t)(32 * w + r32) * 256 + hi * 8;
; #pragma unroll
;         for (int st = 0; st < 16; ++st) {
;             const v8s af = *(const LAS v8s*)(HID + r32 * 264 + st * 16 + hi * 8);
;             const v8s bfr = *(const v8s*)(B2 + st * 16);
;             o = mfma32(af, bfr, o);
;         }
; #pragma unroll
;         for (int r = 0; r < 16; ++r) { const int nl = crow(r, hi); const bool valid = (ch * 32 + nl) < 255;
;             OUT[(size_t)nl * 64 + 32 * w + r32] = valid ? (bf16_t)(pkbf(o[r], 0.f) & 0xffffu) : (bf16_t)0; }
;     }
	s_cbranch_scc0 .LBB0_410
	s_and_b32 s16, s28, 1
	s_lshl_b32 s11, s11, 9
	s_lshl_b32 s16, s16, 8
	s_or_b32 s11, s11, s16
	s_or_b32 s11, s11, s27
	s_lshl_b64 s[12:13], s[12:13], 15
	s_and_b64 s[14:15], s[14:15], exec
	s_cselect_b32 s16, s22, s24
	s_cselect_b32 s17, s21, s23
	s_add_u32 s14, s19, s12
	s_addc_u32 s15, s20, s13
	v_lshlrev_b64 v[2:3], 9, v[34:35]
	v_lshl_add_u64 v[2:3], s[14:15], 0, v[2:3]
	v_lshlrev_b32_e32 v30, 7, v18
	v_or_b32_e32 v20, 27, v18
	v_lshl_add_u64 v[18:19], v[2:3], 0, v[0:1]
	v_mul_u32_u24_e32 v2, 0x210, v41
	v_add3_u32 v0, 0, v2, v0
	global_load_dwordx4 v[64:67], v[18:19], off
	global_load_dwordx4 v[68:71], v[18:19], off offset:32
	global_load_dwordx4 v[72:75], v[18:19], off offset:64
	global_load_dwordx4 v[76:79], v[18:19], off offset:96
	global_load_dwordx4 v[80:83], v[18:19], off offset:128
	global_load_dwordx4 v[84:87], v[18:19], off offset:160
	global_load_dwordx4 v[88:91], v[18:19], off offset:192
	global_load_dwordx4 v[92:95], v[18:19], off offset:224
	global_load_dwordx4 v[96:99], v[18:19], off offset:256
	global_load_dwordx4 v[100:103], v[18:19], off offset:288
	global_load_dwordx4 v[104:107], v[18:19], off offset:320
	global_load_dwordx4 v[108:111], v[18:19], off offset:352
	global_load_dwordx4 v[112:115], v[18:19], off offset:384
	global_load_dwordx4 v[116:119], v[18:19], off offset:416
	global_load_dwordx4 v[120:123], v[18:19], off offset:448
	global_load_dwordx4 v[124:127], v[18:19], off offset:480
	ds_read_b128 v[128:131], v0
	ds_read_b128 v[132:135], v0 offset:32
	ds_read_b128 v[136:139], v0 offset:64
	ds_read_b128 v[140:143], v0 offset:96
	ds_read_b128 v[144:147], v0 offset:128
	ds_read_b128 v[148:151], v0 offset:160
	ds_read_b128 v[152:155], v0 offset:192
	ds_read_b128 v[156:159], v0 offset:224
	ds_read_b128 v[160:163], v0 offset:256
	ds_read_b128 v[164:167], v0 offset:288
	ds_read_b128 v[168:171], v0 offset:320
	ds_read_b128 v[172:175], v0 offset:352
	ds_read_b128 v[176:179], v0 offset:384
	ds_read_b128 v[180:183], v0 offset:416
	ds_read_b128 v[184:187], v0 offset:448
	ds_read_b128 v[188:191], v0 offset:480
	s_lshl_b32 s11, s11, 7
	s_add_u32 s12, s17, s11
	s_addc_u32 s13, s16, 0
	s_ashr_i32 s11, s10, 31
	s_lshl_b64 s[10:11], s[10:11], 1
	s_add_u32 s10, s12, s10
	s_addc_u32 s11, s13, s11
	v_lshlrev_b32_e32 v0, 1, v41
	v_lshl_add_u64 v[18:19], s[10:11], 0, v[0:1]
	v_lshlrev_b32_e32 v0, 9, v40
	s_movk_i32 s10, 0xff
	s_waitcnt lgkmcnt(0)
	s_waitcnt vmcnt(15)
	v_mfma_f32_32x32x16_bf16 v[2:17], v[128:131], v[64:67], 0
	s_waitcnt vmcnt(14)
	v_mfma_f32_32x32x16_bf16 v[2:17], v[132:135], v[68:71], v[2:17]
	s_waitcnt vmcnt(13)
	v_mfma_f32_32x32x16_bf16 v[2:17], v[136:139], v[72:75], v[2:17]
	s_waitcnt vmcnt(12)
	v_mfma_f32_32x32x16_bf16 v[2:17], v[140:143], v[76:79], v[2:17]
	s_waitcnt vmcnt(11)
	v_mfma_f32_32x32x16_bf16 v[2:17], v[144:147], v[80:83], v[2:17]
	s_waitcnt vmcnt(10)
	v_mfma_f32_32x32x16_bf16 v[2:17], v[148:151], v[84:87], v[2:17]
	s_waitcnt vmcnt(9)
	v_mfma_f32_32x32x16_bf16 v[2:17], v[152:155], v[88:91], v[2:17]
	s_waitcnt vmcnt(8)
	v_mfma_f32_32x32x16_bf16 v[2:17], v[156:159], v[92:95], v[2:17]
	s_waitcnt vmcnt(7)
	v_mfma_f32_32x32x16_bf16 v[2:17], v[160:163], v[96:99], v[2:17]
	s_waitcnt vmcnt(6)
	v_mfma_f32_32x32x16_bf16 v[2:17], v[164:167], v[100:103], v[2:17]
	s_waitcnt vmcnt(5)
	v_mfma_f32_32x32x16_bf16 v[2:17], v[168:171], v[104:107], v[2:17]
	s_waitcnt vmcnt(4)
	v_mfma_f32_32x32x16_bf16 v[2:17], v[172:175], v[108:111], v[2:17]
	s_waitcnt vmcnt(3)
	v_mfma_f32_32x32x16_bf16 v[2:17], v[176:179], v[112:115], v[2:17]
	s_waitcnt vmcnt(2)
	v_mfma_f32_32x32x16_bf16 v[2:17], v[180:183], v[116:119], v[2:17]
	s_waitcnt vmcnt(1)
	v_mfma_f32_32x32x16_bf16 v[2:17], v[184:187], v[120:123], v[2:17]
	s_waitcnt vmcnt(0)
	v_mfma_f32_32x32x16_bf16 v[2:17], v[188:191], v[124:127], v[2:17]
	v_lshl_add_u64 v[22:23], v[18:19], 0, v[0:1]
	v_lshlrev_b32_e32 v0, 7, v21
	s_nop 9
	v_cvt_pk_bf16_f32 v2, v2, s0
	global_store_short v[22:23], v2, off
	v_cvt_pk_bf16_f32 v22, v3, s0
	v_lshl_add_u64 v[2:3], v[18:19], 0, v[0:1]
	v_or_b32_e32 v0, 0x100, v30
	global_store_short v[2:3], v22, off
	v_cvt_pk_bf16_f32 v4, v4, s0
	v_lshl_add_u64 v[2:3], v[18:19], 0, v[0:1]
	v_or_b32_e32 v0, 0x180, v30
	global_store_short v[2:3], v4, off
	v_cvt_pk_bf16_f32 v4, v5, s0
	v_lshl_add_u64 v[2:3], v[18:19], 0, v[0:1]
	v_or_b32_e32 v0, 0x400, v30
	global_store_short v[2:3], v4, off
	v_cvt_pk_bf16_f32 v4, v6, s0
	v_lshl_add_u64 v[2:3], v[18:19], 0, v[0:1]
	v_or_b32_e32 v0, 0x480, v30
	global_store_short v[2:3], v4, off
	v_cvt_pk_bf16_f32 v4, v7, s0
	v_lshl_add_u64 v[2:3], v[18:19], 0, v[0:1]
	v_or_b32_e32 v0, 0x500, v30
	global_store_short v[2:3], v4, off
	v_cvt_pk_bf16_f32 v4, v8, s0
	v_lshl_add_u64 v[2:3], v[18:19], 0, v[0:1]
	v_or_b32_e32 v0, 0x580, v30
	global_store_short v[2:3], v4, off
	v_cvt_pk_bf16_f32 v4, v9, s0
	v_lshl_add_u64 v[2:3], v[18:19], 0, v[0:1]
	v_or_b32_e32 v0, 0x800, v30
	global_store_short v[2:3], v4, off
	v_cvt_pk_bf16_f32 v4, v10, s0
	v_lshl_add_u64 v[2:3], v[18:19], 0, v[0:1]
	v_or_b32_e32 v0, 0x880, v30
	global_store_short v[2:3], v4, off
	v_cvt_pk_bf16_f32 v4, v11, s0
	v_lshl_add_u64 v[2:3], v[18:19], 0, v[0:1]
	v_or_b32_e32 v0, 0x900, v30
	global_store_short v[2:3], v4, off
	v_cvt_pk_bf16_f32 v4, v12, s0
	v_lshl_add_u64 v[2:3], v[18:19], 0, v[0:1]
	v_or_b32_e32 v0, 0x980, v30
	global_store_short v[2:3], v4, off
	v_cvt_pk_bf16_f32 v4, v13, s0
	v_lshl_add_u64 v[2:3], v[18:19], 0, v[0:1]
	v_or_b32_e32 v0, 0xc00, v30
	global_store_short v[2:3], v4, off
	v_cvt_pk_bf16_f32 v4, v14, s0
	v_lshl_add_u64 v[2:3], v[18:19], 0, v[0:1]
	v_or_b32_e32 v0, 0xc80, v30
	global_store_short v[2:3], v4, off
	v_cvt_pk_bf16_f32 v4, v15, s0
	v_lshl_add_u64 v[2:3], v[18:19], 0, v[0:1]
	v_or_b32_e32 v0, 0xd00, v30
	global_store_short v[2:3], v4, off
	v_cvt_pk_bf16_f32 v4, v16, s0
	v_lshl_add_u64 v[2:3], v[18:19], 0, v[0:1]
	v_or_b32_e32 v0, s27, v20
	global_store_short v[2:3], v4, off
	v_cvt_pk_bf16_f32 v2, v17, s0
	v_cmp_ne_u32_e32 vcc, s10, v0
	v_lshlrev_b32_e32 v0, 7, v20
	s_nop 0
	v_cndmask_b32_e32 v4, 0, v2, vcc
	v_lshl_add_u64 v[2:3], v[18:19], 0, v[0:1]
	global_store_short v[2:3], v4, off
	s_branch .LBB0_410
